# residual GEMM phases: useless tail staging loads replaced by coalesced stand-in dword loads
# speedup vs baseline: 1.0158x; 1.0158x over previous
;     __device__ __forceinline__ void init(f32x4 (&acc)[2][2][4][2], const Unit& u, int wr, int wc, int fr, int fq) const {
;         const int col0 = u.pn * BM + wc * 32 + 8 * fq;
; #pragma unroll
;         for (int ai = 0; ai < 2; ++ai)
; #pragma unroll
;             for (int m = 0; m < 4; ++m) { const size_t off = (size_t)(u.pm * BM + ai * HALF + wr * 64 + m * 16 + fr) * ldc + col0;
; #pragma unroll
;                 for (int bj = 0; bj < 2; ++bj) { const size_t p = off + bj * HALF;
;                     if (base32) { acc[ai][bj][m][0] = *(const f32x4*)(base32 + p); acc[ai][bj][m][1] = *(const f32x4*)(base32 + p + 4); }
;                     else { const u32x4 r = *(const u32x4*)(xn + p); acc[ai][bj][m][0] = (f32x4){__uint_as_float(r.x << 16), __uint_as_float(r.x & 0xffff0000u), __uint_as_float(r.y << 16), __uint_as_float(r.y & 0xffff0000u)};
;                         acc[ai][bj][m][1] = (f32x4){__uint_as_float(r.z << 16), __uint_as_float(r.z & 0xffff0000u), __uint_as_float(r.w << 16), __uint_as_float(r.w & 0xffff0000u)}; } } }
; template <class Epi, class Sched, bool ALIGN_EPI = false, bool SP2 = false>
; __device__ __forceinline__ void gemm_phase(PG8_LAS unsigned char* lds, const Gemm g, const Sched& S, const Epi& E, const int tid_in) {
;     const int tid = tid_in, wid = __builtin_amdgcn_readfirstlane(tid >> 6), lane = tid & 63, wr = wid >> 2, wc = wid & 3, fr = lane & 15, fq = lane >> 4;
;     const int K = g.K, nt = K / BK;
;     unsigned voffA[2], voffB[2];
; #pragma unroll
;     for (int i = 0; i < 2; ++i) { int R, C; stage_rc(tid * 16 + i * 8192, R, C); const int Rb = Epi::PERM ? ((R & ~31) + perm32(R & 31)) : R;
;         voffA[i] = (unsigned)(R * g.lda + C) * 2u; voffB[i] = (unsigned)(Rb * K + C) * 2u; }
;     const size_t kstep = (size_t)(BK * 2);
;     const size_t hstepB = (size_t)HALF * K * 2, hstepA = (size_t)HALF * g.lda * 2;
;     const size_t tstepB = 2 * hstepB, tstepA = 2 * hstepA;
;     const unsigned ldsw = (unsigned)wid * 1024u;
;     const int aoff = lds_byte(wr * 64 + fr, fq * 8), boff = lds_byte(wc * 32 + fr, fq * 8);
.LBB0_493:
	s_cmp_le_i32 s92, s48
	s_cselect_b64 s[0:1], -1, 0
	s_cmp_lt_i32 s48, s93
	s_cselect_b64 s[4:5], -1, 0
	s_and_b64 s[0:1], s[0:1], s[4:5]
	s_andn2_b64 vcc, exec, s[0:1]
	s_mov_b64 s[0:1], 0
	s_cbranch_vccnz .LBB0_545
	v_mbcnt_lo_u32_b32 v241, -1, 0
	v_mbcnt_hi_u32_b32 v241, -1, v241
	v_lshlrev_b32_e32 v241, 2, v241
	s_mov_b32 s4, -1
	s_load_dwordx2 s[18:19], s[12:13], 0x88
	s_waitcnt vmcnt(0)
	v_mbcnt_lo_u32_b32 v0, s4, 0
	v_mbcnt_hi_u32_b32 v1, s4, v0
	v_readlane_b32 s4, v254, 14
	v_add_u32_e32 v0, s97, v1
	v_readlane_b32 s5, v254, 15
	s_andn2_b64 vcc, exec, s[4:5]
	v_readfirstlane_b32 s6, v0
	s_cbranch_vccnz .LBB0_534
	v_readlane_b32 s4, v255, 5
	s_lshl_b32 s4, s4, 20
	s_and_b32 s4, s4, 0x200000
	v_readlane_b32 s5, v255, 6
	s_waitcnt lgkmcnt(0)
	s_add_u32 s4, s18, s4
	s_addc_u32 s5, s19, 0
	s_add_u32 s48, s4, 0x3000000
	v_bfe_u32 v147, v1, 4, 2
	v_and_b32_e32 v146, 15, v1
	v_lshlrev_b32_e32 v1, 4, v0
	s_addc_u32 s58, s5, 0
	v_add_u32_e32 v2, 0x2000, v1
	s_add_u32 s20, s18, 0x7400000
	v_ashrrev_i32_e32 v3, 31, v2
	s_addc_u32 s21, s19, 0
	s_ashr_i32 s5, s6, 6
	v_lshrrev_b32_e32 v3, 22, v3
	s_and_b32 s8, s5, 3
	v_add_u32_e32 v3, v2, v3
	s_lshl_b32 s59, s5, 10
	s_lshl_b32 s9, s8, 5
	v_ashrrev_i32_e32 v149, 10, v3
	v_readlane_b32 s5, v254, 32
	s_ashr_i32 s4, s6, 8
	v_lshlrev_b32_e32 v148, 3, v147
	v_mul_i32_i24_e32 v3, 0x400, v149
	s_or_b32 s5, s5, s9
	v_lshl_or_b32 v144, s4, 6, v146
	v_sub_u32_e32 v10, v2, v3
	v_or_b32_e32 v2, s5, v148
	v_readlane_b32 s5, v254, 36
	v_lshrrev_b32_e32 v11, 4, v10
	v_ashrrev_i32_e32 v3, 31, v2
	v_add_u32_e32 v8, s5, v144
	v_ashrrev_i32_e32 v9, 31, v8
	v_lshlrev_b64 v[4:5], 11, v[8:9]
	v_bitop3_b32 v9, v11, v10, 32 bitop3:0x6c
	v_ashrrev_i32_e32 v10, 31, v9
	v_lshrrev_b32_e32 v10, 26, v10
	v_add_u32_e32 v10, v9, v10
	v_lshlrev_b32_e32 v11, 3, v149
	v_ashrrev_i32_e32 v150, 6, v10
	v_and_b32_e32 v11, -16, v11
	v_add_u32_e32 v11, v150, v11
	v_and_b32_e32 v12, 3, v150
	s_mov_b32 s5, 0x1fffe0
	v_lshl_add_u64 v[4:5], s[20:21], 0, v[4:5]
	v_lshlrev_b64 v[34:35], 1, v[2:3]
	v_and_or_b32 v16, v11, s5, v12
	v_lshrrev_b32_e32 v12, 2, v11
	v_and_b32_e32 v10, 0xc0, v10
	v_lshl_add_u64 v[2:3], v[4:5], 0, v[34:35]
	v_and_b32_e32 v17, 4, v12
	v_lshlrev_b32_e32 v12, 1, v11
	v_sub_u32_e32 v9, v9, v10
	global_load_dwordx4 v[4:7], v[2:3], off
	v_and_b32_e32 v18, 24, v12
	global_load_dwordx4 v[12:15], v[2:3], off offset:256
	v_lshlrev_b32_e32 v3, 5, v149
	v_ashrrev_i16_sdwa v9, v233, sext(v9) dst_sel:DWORD dst_unused:UNUSED_PAD src0_sel:DWORD src1_sel:BYTE_0
	v_and_b32_e32 v3, 32, v3
	v_bfe_i32 v151, v9, 0, 16
	v_or3_b32 v2, v16, v17, v18
	v_add_lshl_u32 v9, v3, v151, 1
	v_lshl_add_u32 v112, v2, 11, v9
	v_lshl_add_u32 v132, v11, 11, v9
	v_bfe_i32 v9, v0, 27, 1
	v_lshrrev_b32_e32 v9, 22, v9
	v_add_u32_e32 v9, v1, v9
	v_and_b32_e32 v9, 0xfffffc00, v9
	v_add_u32_e32 v2, 16, v8
	v_sub_u32_e32 v1, v1, v9
	v_ashrrev_i32_e32 v3, 31, v2
	v_lshrrev_b32_e32 v9, 4, v1
	v_lshlrev_b64 v[2:3], 11, v[2:3]
	v_bitop3_b32 v9, v9, v1, 32 bitop3:0x6c
	v_lshl_add_u64 v[2:3], s[20:21], 0, v[2:3]
	v_ashrrev_i32_e32 v1, 31, v9
	v_lshl_add_u64 v[2:3], v[2:3], 0, v[34:35]
	v_lshrrev_b32_e32 v1, 26, v1
	global_load_dwordx4 v[20:23], v[2:3], off
	global_load_dwordx4 v[28:31], v[2:3], off offset:256
	v_add_u32_e32 v2, v9, v1
	v_ashrrev_i32_e32 v1, 31, v0
	v_lshrrev_b32_e32 v1, 26, v1
	v_add_u32_e32 v0, v0, v1
	v_ashrrev_i32_e32 v153, 6, v0
	v_add_u32_e32 v0, 32, v8
	v_ashrrev_i32_e32 v1, 31, v0
	v_lshlrev_b64 v[0:1], 11, v[0:1]
	v_ashrrev_i32_e32 v152, 6, v2
	v_lshl_add_u64 v[0:1], s[20:21], 0, v[0:1]
	v_and_b32_e32 v2, 0xc0, v2
	v_lshl_add_u64 v[0:1], v[0:1], 0, v[34:35]
	v_sub_u32_e32 v2, v9, v2
	global_load_dwordx4 v[36:39], v[0:1], off
	global_load_dwordx4 v[44:47], v[0:1], off offset:256
	v_ashrrev_i16_sdwa v0, v233, sext(v2) dst_sel:DWORD dst_unused:UNUSED_PAD src0_sel:DWORD src1_sel:BYTE_0
	v_bfe_i32 v154, v0, 0, 16
	v_add_u32_e32 v0, 48, v8
	v_lshlrev_b32_e32 v3, 3, v153
	v_ashrrev_i32_e32 v1, 31, v0
	v_and_b32_e32 v3, -16, v3
	v_lshlrev_b64 v[0:1], 11, v[0:1]
	v_add_u32_e32 v3, v152, v3
	v_and_b32_e32 v10, 3, v152
	v_lshl_add_u64 v[0:1], s[20:21], 0, v[0:1]
	v_and_or_b32 v10, v3, s5, v10
	v_lshl_add_u64 v[8:9], v[0:1], 0, v[34:35]
	v_readlane_b32 s5, v254, 33
	global_load_dwordx4 v[52:55], v[8:9], off
	global_load_dwordx4 v[60:63], v[8:9], off offset:256
	v_add_u32_e32 v8, s5, v144
	v_ashrrev_i32_e32 v9, 31, v8
	v_lshrrev_b32_e32 v11, 2, v3
	v_lshlrev_b32_e32 v16, 1, v3
	v_lshlrev_b64 v[8:9], 11, v[8:9]
	v_and_b32_e32 v11, 4, v11
	v_and_b32_e32 v16, 24, v16
	v_lshl_add_u64 v[8:9], s[20:21], 0, v[8:9]
	v_or3_b32 v10, v10, v11, v16
	v_lshl_add_u64 v[16:17], v[8:9], 0, v[34:35]
	v_readlane_b32 s5, v254, 34
	global_load_dwordx4 v[68:71], v[16:17], off
	global_load_dwordx4 v[76:79], v[16:17], off offset:256
	v_add_u32_e32 v16, s5, v144
	v_readlane_b32 s5, v254, 35
	v_ashrrev_i32_e32 v17, 31, v16
	v_lshlrev_b64 v[16:17], 11, v[16:17]
	v_add_u32_e32 v26, s5, v144
	v_readlane_b32 s5, v254, 37
	v_ashrrev_i32_e32 v27, 31, v26
	v_lshlrev_b64 v[26:27], 11, v[26:27]
	v_add_u32_e32 v40, s5, v144
	v_ashrrev_i32_e32 v41, 31, v40
	v_lshlrev_b64 v[40:41], 11, v[40:41]
	v_lshl_add_u64 v[16:17], s[20:21], 0, v[16:17]
	v_lshl_add_u64 v[26:27], s[20:21], 0, v[26:27]
	v_lshl_add_u64 v[40:41], s[20:21], 0, v[40:41]
	v_lshl_add_u64 v[24:25], v[16:17], 0, v[34:35]
	v_lshl_add_u64 v[32:33], v[26:27], 0, v[34:35]
	v_lshl_add_u64 v[42:43], v[40:41], 0, v[34:35]
	global_load_dwordx4 v[84:87], v[24:25], off
	global_load_dwordx4 v[92:95], v[24:25], off offset:256
	global_load_dwordx4 v[100:103], v[32:33], off
	global_load_dwordx4 v[108:111], v[32:33], off offset:256
; #define PG8_STAGE(bufoff, gbase, voff) do { _Pragma("unroll") for (int _i = 0; _i < 2; ++_i) \
;         __builtin_amdgcn_global_load_lds((const unsigned*)((const char*)(gbase) + (voff)[_i]), (PG8_LAS unsigned*)(lds + (bufoff) + ldsw + _i * 8192), 16, 0, 0); } while (0)
; #define PG8_WAIT_V(n) asm volatile("s_waitcnt vmcnt(" #n ")" ::: "memory")
; #define PG8_BAR __builtin_amdgcn_s_barrier()
;     __device__ __forceinline__ void init(f32x4 (&acc)[2][2][4][2], const Unit& u, int wr, int wc, int fr, int fq) const {
;     ...
;             for (int m = 0; m < 4; ++m) { const size_t off = (size_t)(u.pm * BM + ai * HALF + wr * 64 + m * 16 + fr) * ldc + col0;
; #pragma unroll
;                 for (int bj = 0; bj < 2; ++bj) { const size_t p = off + bj * HALF;
;                     if (base32) { acc[ai][bj][m][0] = *(const f32x4*)(base32 + p); acc[ai][bj][m][1] = *(const f32x4*)(base32 + p + 4); }
;                     else { const u32x4 r = *(const u32x4*)(xn + p); acc[ai][bj][m][0] = (f32x4){__uint_as_float(r.x << 16), __uint_as_float(r.x & 0xffff0000u), __uint_as_float(r.y << 16), __uint_as_float(r.y & 0xffff0000u)};
;                         acc[ai][bj][m][1] = (f32x4){__uint_as_float(r.z << 16), __uint_as_float(r.z & 0xffff0000u), __uint_as_float(r.w << 16), __uint_as_float(r.w & 0xffff0000u)}; } } }
; #pragma unroll
;         for (int ai = 0; ai < 2; ++ai)
; #pragma unroll
;             for (int bj = 0; bj < 2; ++bj)
; #pragma unroll
;                 for (int m = 0; m < 4; ++m) asm volatile("" : "+v"(acc[ai][bj][m][0]), "+v"(acc[ai][bj][m][1]));
; template <class Epi, class Sched, bool ALIGN_EPI = false, bool SP2 = false>
; __device__ __forceinline__ void gemm_phase(PG8_LAS unsigned char* lds, const Gemm g, const Sched& S, const Epi& E, const int tid_in) {
;     ...
;     const char* cA = (const char*)g.A + (size_t)cur.pm * tstepA + (size_t)(cur.pm >> 3) * g.abx; const char* cB = (const char*)g.Bt + (size_t)cur.pn * tstepB;
;     S.a_ready(cur);
;     if constexpr (SP2) {
;         PG8_STAGE(PG8_SB(0, 0), cB, voffB); PG8_STAGE(PG8_SB(0, 1), cB + hstepB, voffB); PG8_STAGE(PG8_SA(0, 0), cA, voffA); PG8_STAGE(PG8_SA(0, 1), cA + hstepA, voffA);
;         if (wr == 1) PG8_BAR;
;         PG8_WAIT_V(2); PG8_BAR;
	global_load_dwordx4 v[120:123], v[42:43], off
	global_load_dwordx4 v[128:131], v[42:43], off offset:256
	v_lshlrev_b32_e32 v11, 5, v153
	v_readlane_b32 s14, v254, 42
	v_and_b32_e32 v11, 32, v11
	v_readlane_b32 s15, v254, 43
	s_add_u32 s54, s48, s14
	v_add_lshl_u32 v2, v11, v154, 1
	s_addc_u32 s55, s58, s15
	s_add_i32 s60, s59, 0
	v_lshl_add_u32 v114, v10, 11, v2
	v_lshl_add_u32 v134, v3, 11, v2
	s_add_i32 m0, s60, 0x10000
	s_nop 0
	global_load_lds_dwordx4 v114, s[54:55]
	s_add_i32 m0, s60, 0x12000
	v_readlane_b32 s14, v254, 38
	v_readlane_b32 s15, v254, 39
	s_add_u32 s5, s64, s14
	s_addc_u32 s7, s65, s15
	s_add_u32 s14, s54, 0x40000
	global_load_lds_dwordx4 v112, s[54:55]
	s_addc_u32 s15, s55, 0
	s_add_i32 m0, s60, 0x14000
	v_mov_b32_e32 v113, v115
	global_load_lds_dwordx4 v114, s[14:15]
	s_add_i32 m0, s60, 0x16000
	v_mov_b32_e32 v135, v115
	global_load_lds_dwordx4 v112, s[14:15]
	v_readlane_b32 s14, v254, 41
	s_add_u32 s50, s5, s14
	v_readlane_b32 s5, v254, 40
	s_addc_u32 s51, s7, s5
	s_add_i32 s61, s60, 0x2000
	s_mov_b32 m0, s60
	s_add_u32 s14, s50, 0x40000
	global_load_lds_dwordx4 v134, s[50:51]
	s_mov_b32 m0, s61
	s_addc_u32 s15, s51, 0
	s_add_i32 s62, s60, 0x4000
	global_load_lds_dwordx4 v132, s[50:51]
	s_mov_b32 m0, s62
	s_add_i32 s63, s60, 0x6000
	global_load_lds_dwordx4 v134, s[14:15]
	s_mov_b32 m0, s63
	v_mov_b32_e32 v133, v115
	global_load_lds_dwordx4 v132, s[14:15]
	s_waitcnt vmcnt(23)
	v_lshlrev_b32_e32 v0, 16, v4
	v_and_b32_e32 v1, 0xffff0000, v4
	v_lshlrev_b32_e32 v2, 16, v5
	v_and_b32_e32 v3, 0xffff0000, v5
	v_lshlrev_b32_e32 v4, 16, v6
	v_and_b32_e32 v5, 0xffff0000, v6
	v_lshlrev_b32_e32 v6, 16, v7
	v_and_b32_e32 v7, 0xffff0000, v7
	s_waitcnt vmcnt(22)
	v_lshlrev_b32_e32 v8, 16, v12
	v_and_b32_e32 v9, 0xffff0000, v12
	v_lshlrev_b32_e32 v10, 16, v13
	v_and_b32_e32 v11, 0xffff0000, v13
	v_lshlrev_b32_e32 v12, 16, v14
	v_and_b32_e32 v13, 0xffff0000, v14
	v_lshlrev_b32_e32 v14, 16, v15
	v_and_b32_e32 v15, 0xffff0000, v15
	s_waitcnt vmcnt(21)
	v_lshlrev_b32_e32 v16, 16, v20
	v_and_b32_e32 v17, 0xffff0000, v20
	v_lshlrev_b32_e32 v18, 16, v21
	v_and_b32_e32 v19, 0xffff0000, v21
	v_lshlrev_b32_e32 v20, 16, v22
	v_and_b32_e32 v21, 0xffff0000, v22
	v_lshlrev_b32_e32 v22, 16, v23
	v_and_b32_e32 v23, 0xffff0000, v23
	s_waitcnt vmcnt(20)
	v_lshlrev_b32_e32 v24, 16, v28
	v_and_b32_e32 v25, 0xffff0000, v28
	v_lshlrev_b32_e32 v26, 16, v29
	v_and_b32_e32 v27, 0xffff0000, v29
	v_lshlrev_b32_e32 v28, 16, v30
	v_and_b32_e32 v29, 0xffff0000, v30
	v_lshlrev_b32_e32 v30, 16, v31
	v_and_b32_e32 v31, 0xffff0000, v31
	s_waitcnt vmcnt(19)
	v_lshlrev_b32_e32 v32, 16, v36
	v_and_b32_e32 v33, 0xffff0000, v36
	v_lshlrev_b32_e32 v34, 16, v37
	v_and_b32_e32 v35, 0xffff0000, v37
	v_lshlrev_b32_e32 v36, 16, v38
	v_and_b32_e32 v37, 0xffff0000, v38
	v_lshlrev_b32_e32 v38, 16, v39
	v_and_b32_e32 v39, 0xffff0000, v39
	s_waitcnt vmcnt(18)
	v_lshlrev_b32_e32 v40, 16, v44
	v_and_b32_e32 v41, 0xffff0000, v44
	v_lshlrev_b32_e32 v42, 16, v45
	v_and_b32_e32 v43, 0xffff0000, v45
	v_lshlrev_b32_e32 v44, 16, v46
	v_and_b32_e32 v45, 0xffff0000, v46
	v_lshlrev_b32_e32 v46, 16, v47
	v_and_b32_e32 v47, 0xffff0000, v47
	s_waitcnt vmcnt(17)
	v_lshlrev_b32_e32 v48, 16, v52
	v_and_b32_e32 v49, 0xffff0000, v52
	v_lshlrev_b32_e32 v50, 16, v53
	v_and_b32_e32 v51, 0xffff0000, v53
	v_lshlrev_b32_e32 v52, 16, v54
	v_and_b32_e32 v53, 0xffff0000, v54
	v_lshlrev_b32_e32 v54, 16, v55
	v_and_b32_e32 v55, 0xffff0000, v55
	s_waitcnt vmcnt(16)
	v_lshlrev_b32_e32 v56, 16, v60
	v_and_b32_e32 v57, 0xffff0000, v60
	v_lshlrev_b32_e32 v58, 16, v61
	v_and_b32_e32 v59, 0xffff0000, v61
	v_lshlrev_b32_e32 v60, 16, v62
	v_and_b32_e32 v61, 0xffff0000, v62
	v_lshlrev_b32_e32 v62, 16, v63
	v_and_b32_e32 v63, 0xffff0000, v63
	s_waitcnt vmcnt(15)
	v_lshlrev_b32_e32 v64, 16, v68
	v_and_b32_e32 v65, 0xffff0000, v68
	v_lshlrev_b32_e32 v66, 16, v69
	v_and_b32_e32 v67, 0xffff0000, v69
	v_lshlrev_b32_e32 v68, 16, v70
	v_and_b32_e32 v69, 0xffff0000, v70
	v_lshlrev_b32_e32 v70, 16, v71
	v_and_b32_e32 v71, 0xffff0000, v71
	s_waitcnt vmcnt(14)
	v_lshlrev_b32_e32 v72, 16, v76
	v_and_b32_e32 v73, 0xffff0000, v76
	v_lshlrev_b32_e32 v74, 16, v77
	v_and_b32_e32 v75, 0xffff0000, v77
	v_lshlrev_b32_e32 v76, 16, v78
	v_and_b32_e32 v77, 0xffff0000, v78
	v_lshlrev_b32_e32 v78, 16, v79
	v_and_b32_e32 v79, 0xffff0000, v79
	s_waitcnt vmcnt(13)
	v_lshlrev_b32_e32 v80, 16, v84
	v_and_b32_e32 v81, 0xffff0000, v84
	v_lshlrev_b32_e32 v82, 16, v85
	v_and_b32_e32 v83, 0xffff0000, v85
	v_lshlrev_b32_e32 v84, 16, v86
	v_and_b32_e32 v85, 0xffff0000, v86
	v_lshlrev_b32_e32 v86, 16, v87
	v_and_b32_e32 v87, 0xffff0000, v87
	s_waitcnt vmcnt(12)
	v_lshlrev_b32_e32 v88, 16, v92
	v_and_b32_e32 v89, 0xffff0000, v92
	v_lshlrev_b32_e32 v90, 16, v93
	v_and_b32_e32 v91, 0xffff0000, v93
	v_lshlrev_b32_e32 v92, 16, v94
	v_and_b32_e32 v93, 0xffff0000, v94
	v_lshlrev_b32_e32 v94, 16, v95
	v_and_b32_e32 v95, 0xffff0000, v95
	s_waitcnt vmcnt(11)
	v_lshlrev_b32_e32 v96, 16, v100
	v_and_b32_e32 v97, 0xffff0000, v100
	v_lshlrev_b32_e32 v98, 16, v101
	v_and_b32_e32 v99, 0xffff0000, v101
	v_lshlrev_b32_e32 v100, 16, v102
	v_and_b32_e32 v101, 0xffff0000, v102
	v_lshlrev_b32_e32 v102, 16, v103
	v_and_b32_e32 v103, 0xffff0000, v103
	s_waitcnt vmcnt(10)
	v_lshlrev_b32_e32 v104, 16, v108
	v_and_b32_e32 v105, 0xffff0000, v108
	v_lshlrev_b32_e32 v106, 16, v109
	v_and_b32_e32 v107, 0xffff0000, v109
	v_lshlrev_b32_e32 v108, 16, v110
	v_and_b32_e32 v109, 0xffff0000, v110
	v_lshlrev_b32_e32 v110, 16, v111
	v_and_b32_e32 v111, 0xffff0000, v111
	s_waitcnt vmcnt(9)
	v_lshlrev_b32_e32 v116, 16, v120
	v_and_b32_e32 v117, 0xffff0000, v120
	v_lshlrev_b32_e32 v118, 16, v121
	v_and_b32_e32 v119, 0xffff0000, v121
	v_lshlrev_b32_e32 v120, 16, v122
	v_and_b32_e32 v121, 0xffff0000, v122
	v_lshlrev_b32_e32 v122, 16, v123
	v_and_b32_e32 v123, 0xffff0000, v123
	s_waitcnt vmcnt(8)
	v_lshlrev_b32_e32 v124, 16, v128
	v_and_b32_e32 v125, 0xffff0000, v128
	v_lshlrev_b32_e32 v126, 16, v129
	v_and_b32_e32 v127, 0xffff0000, v129
	v_lshlrev_b32_e32 v128, 16, v130
	v_and_b32_e32 v129, 0xffff0000, v130
	v_lshlrev_b32_e32 v130, 16, v131
	v_and_b32_e32 v131, 0xffff0000, v131
	s_cmp_eq_u32 s4, 1
	v_lshl_add_u64 v[142:143], s[54:55], 0, v[114:115]
	v_lshl_add_u64 v[140:141], s[54:55], 0, v[112:113]
	v_lshl_add_u64 v[136:137], s[50:51], 0, v[134:135]
	s_cselect_b64 s[22:23], -1, 0
	s_cmp_lg_u32 s4, 1
	v_lshl_add_u64 v[138:139], s[50:51], 0, v[132:133]
	s_cbranch_scc1 .LBB0_497
	s_barrier

; template <class Epi, class Sched, bool ALIGN_EPI = false, bool SP2 = false>
; __device__ __forceinline__ void gemm_phase(PG8_LAS unsigned char* lds, const Gemm g, const Sched& S, const Epi& E, const int tid_in) {
;     ...
;         const char* nA = has_next ? (const char*)g.A + (size_t)nxt.pm * tstepA + (size_t)(nxt.pm >> 3) * g.abx : cA; const char* nB = has_next ? (const char*)g.Bt + (size_t)nxt.pn * tstepB : cB;
;         for (int t = 0; t < nt; t += 2) {
;             const bool last = (t == nt - 2);
;             const char* a1 = cA + (size_t)(t + 1) * kstep;
;             const char* a2 = last ? nA : cA + (size_t)(t + 2) * kstep; const char* b2 = last ? nB : cB + (size_t)(t + 2) * kstep;
;             const char* a3 = a2 + kstep; const char* b3 = b2 + kstep;
.LBB0_507:
	s_add_u32 s43, s54, 0x100
	s_addc_u32 s73, s55, 0
	s_ashr_i32 s29, s28, 31
	s_lshl_b64 s[14:15], s[28:29], 19
	s_add_u32 s44, s48, s14
	s_addc_u32 s45, s58, s15
	s_and_b64 s[14:15], s[40:41], exec
	s_cselect_b32 s14, s45, s55
	s_cselect_b32 s15, s44, s54
	s_add_u32 s40, s50, 0x40080
	s_addc_u32 s41, s51, 0
	v_lshl_add_u64 v[140:141], s[40:41], 0, v[136:137]
	v_lshl_add_u64 v[142:143], s[40:41], 0, v[138:139]
	s_mov_b32 s29, -2
	s_mov_b64 s[40:41], 0
	s_branch .LBB0_508
.Ltl_foxout_2_s:
	global_load_dword v240, v241, s[54:55]
	s_branch .Ltl_foxout_2_j

; #define PG8_STAGE(bufoff, gbase, voff) do { _Pragma("unroll") for (int _i = 0; _i < 2; ++_i) \
;         __builtin_amdgcn_global_load_lds((const unsigned*)((const char*)(gbase) + (voff)[_i]), (PG8_LAS unsigned*)(lds + (bufoff) + ldsw + _i * 8192), 16, 0, 0); } while (0)
; #define PG8_LDA(dst, b, h) do { _Pragma("unroll") for (int m = 0; m < 4; ++m) _Pragma("unroll") for (int k = 0; k < 2; ++k) dst[m][k] = *(const PG8_LAS bf16x8*)(lds + PG8_SA(b, h) + aoff + m * 2048 + k * 1024); } while (0)
; #define PG8_LDB(dst, b, h) do { _Pragma("unroll") for (int n = 0; n < 2; ++n) _Pragma("unroll") for (int k = 0; k < 2; ++k) dst[n][k] = *(const PG8_LAS bf16x8*)(lds + PG8_SB(b, h) + boff + n * 2048 + k * 1024); } while (0)
; #define PG8_MMA(ai, bj, At, Bt) do { __builtin_amdgcn_s_setprio(1); _Pragma("unroll") for (int m = 0; m < 4; ++m) _Pragma("unroll") for (int n = 0; n < 2; ++n) _Pragma("unroll") for (int k = 0; k < 2; ++k) \
;         acc[ai][bj][m][n] = __builtin_amdgcn_mfma_f32_16x16x32_bf16(Bt[n][k], At[m][k], acc[ai][bj][m][n], 0, 0, 0); __builtin_amdgcn_s_setprio(0); } while (0)
; #define PG8_WAIT_V(n) asm volatile("s_waitcnt vmcnt(" #n ")" ::: "memory")
; #define PG8_WAIT_L(n) asm volatile("s_waitcnt lgkmcnt(" #n ")" ::: "memory")
; #define PG8_BAR __builtin_amdgcn_s_barrier()
; #define PG8_SCHED __builtin_amdgcn_sched_barrier(0)
; template <class Epi, class Sched, bool ALIGN_EPI = false, bool SP2 = false>
; __device__ __forceinline__ void gemm_phase(PG8_LAS unsigned char* lds, const Gemm g, const Sched& S, const Epi& E, const int tid_in) {
;     ...
;             const bool last = (t == nt - 2);
;             const char* a1 = cA + (size_t)(t + 1) * kstep;
;             const char* a2 = last ? nA : cA + (size_t)(t + 2) * kstep; const char* b2 = last ? nB : cB + (size_t)(t + 2) * kstep;
;             const char* a3 = a2 + kstep; const char* b3 = b2 + kstep;
;             if (last && has_next) S.a_ready(nxt);
;             if constexpr (SP2) {
;             PG8_LDB(B0, 0, 0); PG8_LDB(B1, 0, 1); PG8_SCHED; PG8_LDA(At, 0, 0); PG8_STAGE(PG8_SA(1, 1), a1 + hstepA, voffA);
;             PG8_WAIT_V(8); PG8_WAIT_L(0); PG8_BAR; PG8_MMA(0, 0, At, B0); PG8_MMA(0, 1, At, B1); PG8_BAR; PG8_SCHED;
;             PG8_LDA(At, 0, 1); PG8_STAGE(PG8_SB(0, 0), b2, voffB); PG8_STAGE(PG8_SB(0, 1), b2 + hstepB, voffB); PG8_STAGE(PG8_SA(0, 0), a2, voffA);
.LBB0_508:
	s_add_u32 s53, s50, s40
	s_addc_u32 s54, s51, s41
	s_add_u32 s53, s53, 0x100
	s_addc_u32 s54, s54, 0
	s_add_u32 s74, s43, s40
	s_addc_u32 s55, s73, s41
	s_add_i32 s75, 0, 0x10000
	s_cmpk_eq_i32 s40, 0x700
	s_cselect_b32 s57, s47, s54
	s_cselect_b32 s56, s46, s53
	v_add_u32_e32 v151, s75, v145
	s_cselect_b32 s55, s14, s55
	s_cselect_b32 s54, s15, s74
	s_mov_b64 vcc, 0
	s_cmpk_lg_i32 s40, 0x700
	s_cbranch_scc1 .Ltl_foxout_keep
	s_cmp_lg_u32 s100, 0
	s_cbranch_scc1 .Ltl_foxout_keep
	s_mov_b64 vcc, exec
.Ltl_foxout_keep:
	s_add_i32 s53, 0, 0x14000
	ds_read_b128 v[152:155], v151
	ds_read_b128 v[156:159], v151 offset:1024
	ds_read_b128 v[160:163], v151 offset:2048
	ds_read_b128 v[164:167], v151 offset:3072
	v_add_u32_e32 v151, s53, v145
	ds_read_b128 v[168:171], v151
	ds_read_b128 v[172:175], v151 offset:1024
	ds_read_b128 v[176:179], v151 offset:2048
	ds_read_b128 v[180:183], v151 offset:3072
	v_lshl_add_u64 v[216:217], v[140:141], 0, s[40:41]
	s_add_i32 m0, s60, 0xc000
	ds_read_b128 v[184:187], v149
	ds_read_b128 v[188:191], v149 offset:1024
	ds_read_b128 v[192:195], v149 offset:2048
	ds_read_b128 v[196:199], v149 offset:3072
	ds_read_b128 v[200:203], v149 offset:4096
	ds_read_b128 v[204:207], v149 offset:5120
	ds_read_b128 v[208:211], v149 offset:6144
	ds_read_b128 v[212:215], v149 offset:7168
	global_load_lds_dwordx4 v[216:217], off
	v_lshl_add_u64 v[216:217], v[142:143], 0, s[40:41]
	s_add_i32 m0, s60, 0xe000
	s_nop 0
	global_load_lds_dwordx4 v[216:217], off
	s_waitcnt vmcnt(8)
	s_waitcnt lgkmcnt(0)
	s_barrier
	s_setprio 1
	s_waitcnt lgkmcnt(0)
	v_mfma_f32_16x16x32_bf16 v[0:3], v[152:155], v[184:187], v[0:3]
	v_mfma_f32_16x16x32_bf16 v[4:7], v[160:163], v[184:187], v[4:7]
	v_mfma_f32_16x16x32_bf16 v[16:19], v[152:155], v[192:195], v[16:19]
	v_mfma_f32_16x16x32_bf16 v[20:23], v[160:163], v[192:195], v[20:23]
	v_mfma_f32_16x16x32_bf16 v[32:35], v[152:155], v[200:203], v[32:35]
	v_mfma_f32_16x16x32_bf16 v[36:39], v[160:163], v[200:203], v[36:39]
	v_mfma_f32_16x16x32_bf16 v[48:51], v[152:155], v[208:211], v[48:51]
	v_mfma_f32_16x16x32_bf16 v[52:55], v[160:163], v[208:211], v[52:55]
	v_mfma_f32_16x16x32_bf16 v[0:3], v[156:159], v[188:191], v[0:3]
	v_mfma_f32_16x16x32_bf16 v[4:7], v[164:167], v[188:191], v[4:7]
	v_mfma_f32_16x16x32_bf16 v[16:19], v[156:159], v[196:199], v[16:19]
	v_mfma_f32_16x16x32_bf16 v[20:23], v[164:167], v[196:199], v[20:23]
	v_mfma_f32_16x16x32_bf16 v[32:35], v[156:159], v[204:207], v[32:35]
	v_mfma_f32_16x16x32_bf16 v[36:39], v[164:167], v[204:207], v[36:39]
	v_mfma_f32_16x16x32_bf16 v[48:51], v[156:159], v[212:215], v[48:51]
	v_mfma_f32_16x16x32_bf16 v[52:55], v[164:167], v[212:215], v[52:55]
	s_setprio 0
	s_setprio 1
	v_mfma_f32_16x16x32_bf16 v[8:11], v[168:171], v[184:187], v[8:11]
	v_mfma_f32_16x16x32_bf16 v[12:15], v[176:179], v[184:187], v[12:15]
	v_mfma_f32_16x16x32_bf16 v[24:27], v[168:171], v[192:195], v[24:27]
	v_mfma_f32_16x16x32_bf16 v[28:31], v[176:179], v[192:195], v[28:31]
	v_mfma_f32_16x16x32_bf16 v[40:43], v[168:171], v[200:203], v[40:43]
	v_mfma_f32_16x16x32_bf16 v[44:47], v[176:179], v[200:203], v[44:47]
	v_mfma_f32_16x16x32_bf16 v[56:59], v[168:171], v[208:211], v[56:59]
	v_mfma_f32_16x16x32_bf16 v[60:63], v[176:179], v[208:211], v[60:63]
	v_mfma_f32_16x16x32_bf16 v[8:11], v[172:175], v[188:191], v[8:11]
	v_mfma_f32_16x16x32_bf16 v[12:15], v[180:183], v[188:191], v[12:15]
	v_mfma_f32_16x16x32_bf16 v[24:27], v[172:175], v[196:199], v[24:27]
	v_mfma_f32_16x16x32_bf16 v[28:31], v[180:183], v[196:199], v[28:31]
	v_mfma_f32_16x16x32_bf16 v[40:43], v[172:175], v[204:207], v[40:43]
	v_mfma_f32_16x16x32_bf16 v[44:47], v[180:183], v[204:207], v[44:47]
	v_mfma_f32_16x16x32_bf16 v[56:59], v[172:175], v[212:215], v[56:59]
	v_mfma_f32_16x16x32_bf16 v[60:63], v[180:183], v[212:215], v[60:63]
	s_setprio 0
	s_barrier
	s_add_i32 s74, s75, s59
	v_lshl_add_u64 v[216:217], s[54:55], 0, v[114:115]
	s_mov_b32 m0, s74
	ds_read_b128 v[184:187], v149 offset:16384
	ds_read_b128 v[188:191], v149 offset:17408
	ds_read_b128 v[192:195], v149 offset:18432
	ds_read_b128 v[196:199], v149 offset:19456
	ds_read_b128 v[200:203], v149 offset:20480
	ds_read_b128 v[204:207], v149 offset:21504
	ds_read_b128 v[208:211], v149 offset:22528
	ds_read_b128 v[212:215], v149 offset:23552
	s_cbranch_vccnz .Ltl_foxout_2_s
	global_load_lds_dwordx4 v[216:217], off
.Ltl_foxout_2_j:
	s_add_i32 m0, s74, 0x2000
	s_add_u32 s74, s54, 0x40000
	v_lshl_add_u64 v[218:219], s[54:55], 0, v[112:113]
	s_addc_u32 s75, s55, 0
	s_add_i32 s53, s53, s59
	s_cbranch_vccnz .Ltl_foxout_3_s
	global_load_lds_dwordx4 v[218:219], off
.Ltl_foxout_3_j:
	v_lshl_add_u64 v[220:221], s[74:75], 0, v[114:115]
	s_mov_b32 m0, s53
	v_lshl_add_u64 v[222:223], s[56:57], 0, v[132:133]
	s_cbranch_vccnz .Ltl_foxout_4_s
	global_load_lds_dwordx4 v[220:221], off
.Ltl_foxout_4_j:
	v_lshl_add_u64 v[220:221], s[74:75], 0, v[112:113]
	s_add_i32 m0, s53, 0x2000
	s_nop 0
	s_cbranch_vccnz .Ltl_foxout_5_s
	global_load_lds_dwordx4 v[220:221], off
.Ltl_foxout_5_j:
	v_lshl_add_u64 v[220:221], s[56:57], 0, v[134:135]
	s_mov_b32 m0, s60
	s_nop 0
	s_cbranch_vccnz .Ltl_foxout_6_s
	global_load_lds_dwordx4 v[220:221], off
.Ltl_foxout_6_j:
	s_mov_b32 m0, s61
	s_nop 0
	s_cbranch_vccnz .Ltl_foxout_7_s
	global_load_lds_dwordx4 v[222:223], off
; #define PG8_STAGE(bufoff, gbase, voff) do { _Pragma("unroll") for (int _i = 0; _i < 2; ++_i) \
;         __builtin_amdgcn_global_load_lds((const unsigned*)((const char*)(gbase) + (voff)[_i]), (PG8_LAS unsigned*)(lds + (bufoff) + ldsw + _i * 8192), 16, 0, 0); } while (0)
; #define PG8_LDA(dst, b, h) do { _Pragma("unroll") for (int m = 0; m < 4; ++m) _Pragma("unroll") for (int k = 0; k < 2; ++k) dst[m][k] = *(const PG8_LAS bf16x8*)(lds + PG8_SA(b, h) + aoff + m * 2048 + k * 1024); } while (0)
; #define PG8_LDB(dst, b, h) do { _Pragma("unroll") for (int n = 0; n < 2; ++n) _Pragma("unroll") for (int k = 0; k < 2; ++k) dst[n][k] = *(const PG8_LAS bf16x8*)(lds + PG8_SB(b, h) + boff + n * 2048 + k * 1024); } while (0)
; #define PG8_MMA(ai, bj, At, Bt) do { __builtin_amdgcn_s_setprio(1); _Pragma("unroll") for (int m = 0; m < 4; ++m) _Pragma("unroll") for (int n = 0; n < 2; ++n) _Pragma("unroll") for (int k = 0; k < 2; ++k) \
;         acc[ai][bj][m][n] = __builtin_amdgcn_mfma_f32_16x16x32_bf16(Bt[n][k], At[m][k], acc[ai][bj][m][n], 0, 0, 0); __builtin_amdgcn_s_setprio(0); } while (0)
; #define PG8_WAIT_V(n) asm volatile("s_waitcnt vmcnt(" #n ")" ::: "memory")
; #define PG8_WAIT_L(n) asm volatile("s_waitcnt lgkmcnt(" #n ")" ::: "memory")
; #define PG8_BAR __builtin_amdgcn_s_barrier()
; #define PG8_SCHED __builtin_amdgcn_sched_barrier(0)
; template <class Epi, class Sched, bool ALIGN_EPI = false, bool SP2 = false>
; __device__ __forceinline__ void gemm_phase(PG8_LAS unsigned char* lds, const Gemm g, const Sched& S, const Epi& E, const int tid_in) {
;     ...
;             PG8_WAIT_V(8); PG8_WAIT_L(0); PG8_BAR; PG8_MMA(1, 0, At, B0); PG8_MMA(1, 1, At, B1); PG8_BAR; PG8_SCHED;
;             PG8_LDB(B0, 1, 0); PG8_LDB(B1, 1, 1); PG8_SCHED; PG8_LDA(At, 1, 0); PG8_STAGE(PG8_SA(0, 1), a2 + hstepA, voffA);
;             PG8_WAIT_V(8); PG8_WAIT_L(0); PG8_BAR; PG8_MMA(0, 0, At, B0); PG8_MMA(0, 1, At, B1); PG8_BAR; PG8_SCHED;
.Ltl_foxout_7_j:
	s_waitcnt vmcnt(8)
	s_waitcnt lgkmcnt(0)
	s_barrier
	s_setprio 1
	s_waitcnt lgkmcnt(0)
	v_mfma_f32_16x16x32_bf16 v[64:67], v[152:155], v[184:187], v[64:67]
	v_mfma_f32_16x16x32_bf16 v[68:71], v[160:163], v[184:187], v[68:71]
	v_mfma_f32_16x16x32_bf16 v[80:83], v[152:155], v[192:195], v[80:83]
	v_mfma_f32_16x16x32_bf16 v[84:87], v[160:163], v[192:195], v[84:87]
	v_mfma_f32_16x16x32_bf16 v[96:99], v[152:155], v[200:203], v[96:99]
	v_mfma_f32_16x16x32_bf16 v[100:103], v[160:163], v[200:203], v[100:103]
	v_mfma_f32_16x16x32_bf16 v[116:119], v[152:155], v[208:211], v[116:119]
	v_mfma_f32_16x16x32_bf16 v[120:123], v[160:163], v[208:211], v[120:123]
	v_mfma_f32_16x16x32_bf16 v[64:67], v[156:159], v[188:191], v[64:67]
	v_mfma_f32_16x16x32_bf16 v[68:71], v[164:167], v[188:191], v[68:71]
	v_mfma_f32_16x16x32_bf16 v[80:83], v[156:159], v[196:199], v[80:83]
	v_mfma_f32_16x16x32_bf16 v[84:87], v[164:167], v[196:199], v[84:87]
	v_mfma_f32_16x16x32_bf16 v[96:99], v[156:159], v[204:207], v[96:99]
	v_mfma_f32_16x16x32_bf16 v[100:103], v[164:167], v[204:207], v[100:103]
	v_mfma_f32_16x16x32_bf16 v[116:119], v[156:159], v[212:215], v[116:119]
	v_mfma_f32_16x16x32_bf16 v[120:123], v[164:167], v[212:215], v[120:123]
	s_setprio 0
	s_setprio 1
	v_mfma_f32_16x16x32_bf16 v[72:75], v[168:171], v[184:187], v[72:75]
	v_mfma_f32_16x16x32_bf16 v[76:79], v[176:179], v[184:187], v[76:79]
	v_mfma_f32_16x16x32_bf16 v[88:91], v[168:171], v[192:195], v[88:91]
	v_mfma_f32_16x16x32_bf16 v[92:95], v[176:179], v[192:195], v[92:95]
	v_mfma_f32_16x16x32_bf16 v[104:107], v[168:171], v[200:203], v[104:107]
	v_mfma_f32_16x16x32_bf16 v[108:111], v[176:179], v[200:203], v[108:111]
	v_mfma_f32_16x16x32_bf16 v[124:127], v[168:171], v[208:211], v[124:127]
	v_mfma_f32_16x16x32_bf16 v[128:131], v[176:179], v[208:211], v[128:131]
	v_mfma_f32_16x16x32_bf16 v[72:75], v[172:175], v[188:191], v[72:75]
	v_mfma_f32_16x16x32_bf16 v[76:79], v[180:183], v[188:191], v[76:79]
	v_mfma_f32_16x16x32_bf16 v[88:91], v[172:175], v[196:199], v[88:91]
	v_mfma_f32_16x16x32_bf16 v[92:95], v[180:183], v[196:199], v[92:95]
	v_mfma_f32_16x16x32_bf16 v[104:107], v[172:175], v[204:207], v[104:107]
	v_mfma_f32_16x16x32_bf16 v[108:111], v[180:183], v[204:207], v[108:111]
	v_mfma_f32_16x16x32_bf16 v[124:127], v[172:175], v[212:215], v[124:127]
	v_mfma_f32_16x16x32_bf16 v[128:131], v[180:183], v[212:215], v[128:131]
	s_setprio 0
	s_barrier
	s_add_i32 s53, 0, 0x18000
	v_add_u32_e32 v151, s53, v145
	s_add_i32 s74, 0, 0x1c000
	ds_read_b128 v[152:155], v151
	ds_read_b128 v[156:159], v151 offset:1024
	ds_read_b128 v[160:163], v151 offset:2048
	ds_read_b128 v[164:167], v151 offset:3072
	v_add_u32_e32 v151, s74, v145
	ds_read_b128 v[168:171], v151
	ds_read_b128 v[172:175], v151 offset:1024
	ds_read_b128 v[176:179], v151 offset:2048
	ds_read_b128 v[180:183], v151 offset:3072
	s_add_u32 s56, s56, 0x40000
	s_addc_u32 s57, s57, 0
	s_mov_b32 m0, s62
	v_lshl_add_u64 v[224:225], s[56:57], 0, v[134:135]
	ds_read_b128 v[184:187], v149 offset:32768
	ds_read_b128 v[188:191], v149 offset:33792
	ds_read_b128 v[192:195], v149 offset:34816
	ds_read_b128 v[196:199], v149 offset:35840
	ds_read_b128 v[200:203], v149 offset:36864
	ds_read_b128 v[204:207], v149 offset:37888
	ds_read_b128 v[208:211], v149 offset:38912
	ds_read_b128 v[212:215], v149 offset:39936
	s_cbranch_vccnz .Ltl_foxout_8_s
	global_load_lds_dwordx4 v[224:225], off
.Ltl_foxout_8_j:
	v_lshl_add_u64 v[224:225], s[56:57], 0, v[132:133]
	s_mov_b32 m0, s63
	s_nop 0
	s_cbranch_vccnz .Ltl_foxout_9_s
	global_load_lds_dwordx4 v[224:225], off
; #define PG8_STAGE(bufoff, gbase, voff) do { _Pragma("unroll") for (int _i = 0; _i < 2; ++_i) \
;         __builtin_amdgcn_global_load_lds((const unsigned*)((const char*)(gbase) + (voff)[_i]), (PG8_LAS unsigned*)(lds + (bufoff) + ldsw + _i * 8192), 16, 0, 0); } while (0)
; #define PG8_LDA(dst, b, h) do { _Pragma("unroll") for (int m = 0; m < 4; ++m) _Pragma("unroll") for (int k = 0; k < 2; ++k) dst[m][k] = *(const PG8_LAS bf16x8*)(lds + PG8_SA(b, h) + aoff + m * 2048 + k * 1024); } while (0)
; #define PG8_MMA(ai, bj, At, Bt) do { __builtin_amdgcn_s_setprio(1); _Pragma("unroll") for (int m = 0; m < 4; ++m) _Pragma("unroll") for (int n = 0; n < 2; ++n) _Pragma("unroll") for (int k = 0; k < 2; ++k) \
;         acc[ai][bj][m][n] = __builtin_amdgcn_mfma_f32_16x16x32_bf16(Bt[n][k], At[m][k], acc[ai][bj][m][n], 0, 0, 0); __builtin_amdgcn_s_setprio(0); } while (0)
; #define PG8_WAIT_V(n) asm volatile("s_waitcnt vmcnt(" #n ")" ::: "memory")
; #define PG8_WAIT_L(n) asm volatile("s_waitcnt lgkmcnt(" #n ")" ::: "memory")
; #define PG8_BAR __builtin_amdgcn_s_barrier()
; #define PG8_SCHED __builtin_amdgcn_sched_barrier(0)
; template <class Epi, class Sched, bool ALIGN_EPI = false, bool SP2 = false>
; __device__ __forceinline__ void gemm_phase(PG8_LAS unsigned char* lds, const Gemm g, const Sched& S, const Epi& E, const int tid_in) {
;     ...
;             PG8_LDA(At, 1, 1); PG8_STAGE(PG8_SB(1, 0), b3, voffB); PG8_STAGE(PG8_SB(1, 1), b3 + hstepB, voffB); PG8_STAGE(PG8_SA(1, 0), a3, voffA);
;             PG8_WAIT_V(8); PG8_WAIT_L(0); PG8_BAR; PG8_MMA(1, 0, At, B0); PG8_MMA(1, 1, At, B1); PG8_BAR; PG8_SCHED;
.Ltl_foxout_9_j:
	s_waitcnt vmcnt(8)
	s_waitcnt lgkmcnt(0)
	s_barrier
	s_setprio 1
	s_waitcnt lgkmcnt(0)
	v_mfma_f32_16x16x32_bf16 v[0:3], v[152:155], v[184:187], v[0:3]
	v_mfma_f32_16x16x32_bf16 v[4:7], v[160:163], v[184:187], v[4:7]
	v_mfma_f32_16x16x32_bf16 v[16:19], v[152:155], v[192:195], v[16:19]
	v_mfma_f32_16x16x32_bf16 v[20:23], v[160:163], v[192:195], v[20:23]
	v_mfma_f32_16x16x32_bf16 v[32:35], v[152:155], v[200:203], v[32:35]
	v_mfma_f32_16x16x32_bf16 v[36:39], v[160:163], v[200:203], v[36:39]
	v_mfma_f32_16x16x32_bf16 v[48:51], v[152:155], v[208:211], v[48:51]
	v_mfma_f32_16x16x32_bf16 v[52:55], v[160:163], v[208:211], v[52:55]
	v_mfma_f32_16x16x32_bf16 v[0:3], v[156:159], v[188:191], v[0:3]
	v_mfma_f32_16x16x32_bf16 v[4:7], v[164:167], v[188:191], v[4:7]
	v_mfma_f32_16x16x32_bf16 v[16:19], v[156:159], v[196:199], v[16:19]
	v_mfma_f32_16x16x32_bf16 v[20:23], v[164:167], v[196:199], v[20:23]
	v_mfma_f32_16x16x32_bf16 v[32:35], v[156:159], v[204:207], v[32:35]
	v_mfma_f32_16x16x32_bf16 v[36:39], v[164:167], v[204:207], v[36:39]
	v_mfma_f32_16x16x32_bf16 v[48:51], v[156:159], v[212:215], v[48:51]
	v_mfma_f32_16x16x32_bf16 v[52:55], v[164:167], v[212:215], v[52:55]
	s_setprio 0
	s_setprio 1
	v_mfma_f32_16x16x32_bf16 v[8:11], v[168:171], v[184:187], v[8:11]
	v_mfma_f32_16x16x32_bf16 v[12:15], v[176:179], v[184:187], v[12:15]
	v_mfma_f32_16x16x32_bf16 v[24:27], v[168:171], v[192:195], v[24:27]
	v_mfma_f32_16x16x32_bf16 v[28:31], v[176:179], v[192:195], v[28:31]
	v_mfma_f32_16x16x32_bf16 v[40:43], v[168:171], v[200:203], v[40:43]
	v_mfma_f32_16x16x32_bf16 v[44:47], v[176:179], v[200:203], v[44:47]
	v_mfma_f32_16x16x32_bf16 v[56:59], v[168:171], v[208:211], v[56:59]
	v_mfma_f32_16x16x32_bf16 v[60:63], v[176:179], v[208:211], v[60:63]
	v_mfma_f32_16x16x32_bf16 v[8:11], v[172:175], v[188:191], v[8:11]
	v_mfma_f32_16x16x32_bf16 v[12:15], v[180:183], v[188:191], v[12:15]
	v_mfma_f32_16x16x32_bf16 v[24:27], v[172:175], v[196:199], v[24:27]
	v_mfma_f32_16x16x32_bf16 v[28:31], v[180:183], v[196:199], v[28:31]
	v_mfma_f32_16x16x32_bf16 v[40:43], v[172:175], v[204:207], v[40:43]
	v_mfma_f32_16x16x32_bf16 v[44:47], v[180:183], v[204:207], v[44:47]
	v_mfma_f32_16x16x32_bf16 v[56:59], v[172:175], v[212:215], v[56:59]
	v_mfma_f32_16x16x32_bf16 v[60:63], v[180:183], v[212:215], v[60:63]
	s_setprio 0
	s_barrier
	s_add_i32 s53, s53, s59
	v_lshl_add_u64 v[216:217], v[216:217], 0, s[10:11]
	s_mov_b32 m0, s53
	ds_read_b128 v[184:187], v149 offset:49152
	ds_read_b128 v[188:191], v149 offset:50176
	ds_read_b128 v[192:195], v149 offset:51200
	ds_read_b128 v[196:199], v149 offset:52224
	ds_read_b128 v[200:203], v149 offset:53248
	ds_read_b128 v[204:207], v149 offset:54272
	ds_read_b128 v[208:211], v149 offset:55296
	ds_read_b128 v[212:215], v149 offset:56320
	s_cbranch_vccnz .Ltl_foxout_10_s
	global_load_lds_dwordx4 v[216:217], off
.Ltl_foxout_10_j:
	s_add_i32 m0, s53, 0x2000
	s_add_u32 s54, s54, 0x40080
	v_lshl_add_u64 v[216:217], v[218:219], 0, s[10:11]
	s_addc_u32 s55, s55, 0
	s_add_i32 s53, s74, s59
	s_cbranch_vccnz .Ltl_foxout_11_s
	global_load_lds_dwordx4 v[216:217], off
.Ltl_foxout_11_j:
	v_lshl_add_u64 v[216:217], s[54:55], 0, v[114:115]
	s_mov_b32 m0, s53
	s_nop 0
	s_cbranch_vccnz .Ltl_foxout_12_s
	global_load_lds_dwordx4 v[216:217], off
.Ltl_foxout_12_j:
	v_lshl_add_u64 v[216:217], s[54:55], 0, v[112:113]
	s_add_i32 m0, s53, 0x2000
	s_nop 0
	s_cbranch_vccnz .Ltl_foxout_13_s
	global_load_lds_dwordx4 v[216:217], off
.Ltl_foxout_13_j:
	v_lshl_add_u64 v[216:217], v[220:221], 0, s[10:11]
	s_mov_b32 m0, s66
	s_nop 0
	s_cbranch_vccnz .Ltl_foxout_14_s
	global_load_lds_dwordx4 v[216:217], off
.Ltl_foxout_14_j:
	v_lshl_add_u64 v[216:217], v[222:223], 0, s[10:11]
	s_mov_b32 m0, s67
	s_nop 0
	s_cbranch_vccnz .Ltl_foxout_15_s
	global_load_lds_dwordx4 v[216:217], off
.Ltl_foxout_15_j:
	s_waitcnt vmcnt(8)
	s_waitcnt lgkmcnt(0)
	s_barrier
	s_setprio 1
	s_waitcnt lgkmcnt(0)
	v_mfma_f32_16x16x32_bf16 v[64:67], v[152:155], v[184:187], v[64:67]
	v_mfma_f32_16x16x32_bf16 v[68:71], v[160:163], v[184:187], v[68:71]
	v_mfma_f32_16x16x32_bf16 v[80:83], v[152:155], v[192:195], v[80:83]
	v_mfma_f32_16x16x32_bf16 v[84:87], v[160:163], v[192:195], v[84:87]
	v_mfma_f32_16x16x32_bf16 v[96:99], v[152:155], v[200:203], v[96:99]
	v_mfma_f32_16x16x32_bf16 v[100:103], v[160:163], v[200:203], v[100:103]
	v_mfma_f32_16x16x32_bf16 v[116:119], v[152:155], v[208:211], v[116:119]
	v_mfma_f32_16x16x32_bf16 v[120:123], v[160:163], v[208:211], v[120:123]
	v_mfma_f32_16x16x32_bf16 v[64:67], v[156:159], v[188:191], v[64:67]
	v_mfma_f32_16x16x32_bf16 v[68:71], v[164:167], v[188:191], v[68:71]
	v_mfma_f32_16x16x32_bf16 v[80:83], v[156:159], v[196:199], v[80:83]
	v_mfma_f32_16x16x32_bf16 v[84:87], v[164:167], v[196:199], v[84:87]
	v_mfma_f32_16x16x32_bf16 v[96:99], v[156:159], v[204:207], v[96:99]
	v_mfma_f32_16x16x32_bf16 v[100:103], v[164:167], v[204:207], v[100:103]
	v_mfma_f32_16x16x32_bf16 v[116:119], v[156:159], v[212:215], v[116:119]
	v_mfma_f32_16x16x32_bf16 v[120:123], v[164:167], v[212:215], v[120:123]
	s_setprio 0
	s_setprio 1
	v_mfma_f32_16x16x32_bf16 v[72:75], v[168:171], v[184:187], v[72:75]
	v_mfma_f32_16x16x32_bf16 v[76:79], v[176:179], v[184:187], v[76:79]
	v_mfma_f32_16x16x32_bf16 v[88:91], v[168:171], v[192:195], v[88:91]
	v_mfma_f32_16x16x32_bf16 v[92:95], v[176:179], v[192:195], v[92:95]
	v_mfma_f32_16x16x32_bf16 v[104:107], v[168:171], v[200:203], v[104:107]
	v_mfma_f32_16x16x32_bf16 v[108:111], v[176:179], v[200:203], v[108:111]
	v_mfma_f32_16x16x32_bf16 v[124:127], v[168:171], v[208:211], v[124:127]
	v_mfma_f32_16x16x32_bf16 v[128:131], v[176:179], v[208:211], v[128:131]
	v_mfma_f32_16x16x32_bf16 v[72:75], v[172:175], v[188:191], v[72:75]
	v_mfma_f32_16x16x32_bf16 v[76:79], v[180:183], v[188:191], v[76:79]
	v_mfma_f32_16x16x32_bf16 v[88:91], v[172:175], v[196:199], v[88:91]
	v_mfma_f32_16x16x32_bf16 v[92:95], v[180:183], v[196:199], v[92:95]
	v_mfma_f32_16x16x32_bf16 v[104:107], v[172:175], v[204:207], v[104:107]
	v_mfma_f32_16x16x32_bf16 v[108:111], v[180:183], v[204:207], v[108:111]
	v_mfma_f32_16x16x32_bf16 v[124:127], v[172:175], v[212:215], v[124:127]
	v_mfma_f32_16x16x32_bf16 v[128:131], v[180:183], v[212:215], v[128:131]
	s_setprio 0
	s_barrier
	s_add_i32 s29, s29, 2
	s_add_u32 s40, s40, 0x100
	s_addc_u32 s41, s41, 0
	s_cmp_gt_u32 s29, 13
	s_cbranch_scc0 .LBB0_508
	s_and_b64 vcc, exec, s[26:27]
	s_cbranch_vccz .LBB0_511
	s_barrier

;     __device__ __forceinline__ void init(f32x4 (&acc)[2][2][4][2], const Unit& u, int wr, int wc, int fr, int fq) const {
;     ...
;             for (int m = 0; m < 4; ++m) { const size_t off = (size_t)(u.pm * BM + ai * HALF + wr * 64 + m * 16 + fr) * ldc + col0;
; #pragma unroll
;                 for (int bj = 0; bj < 2; ++bj) { const size_t p = off + bj * HALF;
;                     if (base32) { acc[ai][bj][m][0] = *(const f32x4*)(base32 + p); acc[ai][bj][m][1] = *(const f32x4*)(base32 + p + 4); }
;                     else { const u32x4 r = *(const u32x4*)(xn + p); acc[ai][bj][m][0] = (f32x4){__uint_as_float(r.x << 16), __uint_as_float(r.x & 0xffff0000u), __uint_as_float(r.y << 16), __uint_as_float(r.y & 0xffff0000u)};
;                         acc[ai][bj][m][1] = (f32x4){__uint_as_float(r.z << 16), __uint_as_float(r.z & 0xffff0000u), __uint_as_float(r.w << 16), __uint_as_float(r.w & 0xffff0000u)}; } } }
; template <class Epi, class Sched, bool ALIGN_EPI = false, bool SP2 = false>
; __device__ __forceinline__ void gemm_phase(PG8_LAS unsigned char* lds, const Gemm g, const Sched& S, const Epi& E, const int tid_in) {
;     ...
;     for (int i = 0; i < 2; ++i) { int R, C; stage_rc(tid * 16 + i * 8192, R, C); const int Rb = Epi::PERM ? ((R & ~31) + perm32(R & 31)) : R;
;         voffA[i] = (unsigned)(R * g.lda + C) * 2u; voffB[i] = (unsigned)(Rb * K + C) * 2u; }
;     const size_t kstep = (size_t)(BK * 2);
;     const size_t hstepB = (size_t)HALF * K * 2, hstepA = (size_t)HALF * g.lda * 2;
;     const size_t tstepB = 2 * hstepB, tstepA = 2 * hstepA;
;     const unsigned ldsw = (unsigned)wid * 1024u;
;     const int aoff = lds_byte(wr * 64 + fr, fq * 8), boff = lds_byte(wc * 32 + fr, fq * 8);
;     ...
;     Unit cur, nxt; int ui = 0;
;     if (!S.next(0, cur)) return;
;     f32x4 acc[2][2][4][2];
;     if constexpr (Epi::HAS_INIT) { E.init(acc, cur, wr, wc, fr, fq); }
;     else {
; #pragma unroll
;     for (int a = 0; a < 2; ++a)
; #pragma unroll
;         for (int b = 0; b < 2; ++b)
; #pragma unroll
;             for (int m = 0; m < 4; ++m)
; #pragma unroll
;                 for (int n = 0; n < 2; ++n) acc[a][b][m][n] = (f32x4){0.f, 0.f, 0.f, 0.f};
;     }
;     bf16x8 At[4][2], B0[2][2], B1[2][2];
;     const char* cA = (const char*)g.A + (size_t)cur.pm * tstepA + (size_t)(cur.pm >> 3) * g.abx; const char* cB = (const char*)g.Bt + (size_t)cur.pn * tstepB;
;     S.a_ready(cur);
.LBB0_781:
	s_cmp_le_i32 s92, s48
	s_cselect_b64 s[0:1], -1, 0
	s_cmp_lt_i32 s48, s93
	s_cselect_b64 s[4:5], -1, 0
	s_and_b64 s[0:1], s[0:1], s[4:5]
	s_andn2_b64 vcc, exec, s[0:1]
	s_cbranch_vccnz .LBB0_831
	v_mbcnt_lo_u32_b32 v241, -1, 0
	v_mbcnt_hi_u32_b32 v241, -1, v241
	v_lshlrev_b32_e32 v241, 2, v241
	s_mov_b32 s0, -1
	v_readlane_b32 s4, v254, 14
	s_waitcnt vmcnt(0)
	v_mbcnt_lo_u32_b32 v0, s0, 0
	v_mbcnt_hi_u32_b32 v1, s0, v0
	s_load_dwordx2 s[0:1], s[94:95], 0x88
	v_add_u32_e32 v0, s97, v1
	v_readlane_b32 s5, v254, 15
	s_andn2_b64 vcc, exec, s[4:5]
	v_readfirstlane_b32 s6, v0
	s_cbranch_vccnz .LBB0_820
	s_waitcnt lgkmcnt(0)
	s_add_u32 s48, s0, 0x9400000
	s_addc_u32 s54, s1, 0
	s_lshl_b32 s4, s86, 22
	s_add_u32 s4, s0, s4
	s_addc_u32 s5, s1, 0
	s_add_u32 s55, s4, 0x1800000
	v_bfe_u32 v147, v1, 4, 2
	v_and_b32_e32 v146, 15, v1
	v_lshlrev_b32_e32 v1, 4, v0
	s_addc_u32 s56, s5, 0
	v_add_u32_e32 v2, 0x2000, v1
	s_add_u32 s12, s0, 0x7400000
	v_ashrrev_i32_e32 v3, 31, v2
	s_addc_u32 s13, s1, 0
	s_ashr_i32 s5, s6, 6
	v_lshrrev_b32_e32 v3, 22, v3
	s_and_b32 s8, s5, 3
	v_add_u32_e32 v3, v2, v3
	s_lshl_b32 s57, s5, 10
	s_lshl_b32 s9, s8, 5
	v_ashrrev_i32_e32 v149, 10, v3
	v_readlane_b32 s5, v254, 32
	s_ashr_i32 s4, s6, 8
	v_lshlrev_b32_e32 v148, 3, v147
	v_mul_i32_i24_e32 v3, 0x400, v149
	s_or_b32 s5, s5, s9
	v_lshl_or_b32 v144, s4, 6, v146
	v_sub_u32_e32 v10, v2, v3
	v_or_b32_e32 v2, s5, v148
	v_readlane_b32 s5, v254, 36
	v_lshrrev_b32_e32 v11, 4, v10
	v_ashrrev_i32_e32 v3, 31, v2
	v_add_u32_e32 v8, s5, v144
	v_ashrrev_i32_e32 v9, 31, v8
	v_lshlrev_b64 v[4:5], 11, v[8:9]
	v_bitop3_b32 v9, v11, v10, 32 bitop3:0x6c
	v_ashrrev_i32_e32 v10, 31, v9
	v_lshrrev_b32_e32 v10, 26, v10
	v_add_u32_e32 v10, v9, v10
	v_lshlrev_b32_e32 v11, 3, v149
	v_ashrrev_i32_e32 v150, 6, v10
	v_and_b32_e32 v11, -16, v11
	v_add_u32_e32 v11, v150, v11
	v_and_b32_e32 v12, 3, v150
	s_mov_b32 s5, 0xfffe0
	v_lshl_add_u64 v[4:5], s[12:13], 0, v[4:5]
	v_lshlrev_b64 v[34:35], 1, v[2:3]
	v_and_or_b32 v16, v11, s5, v12
	v_lshrrev_b32_e32 v12, 2, v11
	v_and_b32_e32 v10, 0xc0, v10
	v_lshl_add_u64 v[2:3], v[4:5], 0, v[34:35]
	v_and_b32_e32 v17, 4, v12
	v_lshlrev_b32_e32 v12, 1, v11
	v_sub_u32_e32 v9, v9, v10
	global_load_dwordx4 v[4:7], v[2:3], off
	v_and_b32_e32 v18, 24, v12
	global_load_dwordx4 v[12:15], v[2:3], off offset:256
	v_lshlrev_b32_e32 v3, 5, v149
	v_ashrrev_i16_sdwa v9, v233, sext(v9) dst_sel:DWORD dst_unused:UNUSED_PAD src0_sel:DWORD src1_sel:BYTE_0
	v_and_b32_e32 v3, 32, v3
	v_bfe_i32 v151, v9, 0, 16
	v_or3_b32 v2, v16, v17, v18
	v_add_lshl_u32 v9, v3, v151, 1
	v_lshl_add_u32 v112, v2, 12, v9
	v_lshl_add_u32 v132, v11, 13, v9
	v_bfe_i32 v9, v0, 27, 1
	v_lshrrev_b32_e32 v9, 22, v9
	v_add_u32_e32 v9, v1, v9
	v_and_b32_e32 v9, 0xfffffc00, v9
	v_add_u32_e32 v2, 16, v8
	v_sub_u32_e32 v1, v1, v9
	v_ashrrev_i32_e32 v3, 31, v2
	v_lshrrev_b32_e32 v9, 4, v1
	v_lshlrev_b64 v[2:3], 11, v[2:3]
	v_bitop3_b32 v9, v9, v1, 32 bitop3:0x6c
	v_lshl_add_u64 v[2:3], s[12:13], 0, v[2:3]
	v_ashrrev_i32_e32 v1, 31, v9
	v_lshl_add_u64 v[2:3], v[2:3], 0, v[34:35]
	v_lshrrev_b32_e32 v1, 26, v1
	global_load_dwordx4 v[20:23], v[2:3], off
	global_load_dwordx4 v[28:31], v[2:3], off offset:256
	v_add_u32_e32 v2, v9, v1
	v_ashrrev_i32_e32 v1, 31, v0
	v_lshrrev_b32_e32 v1, 26, v1
	v_add_u32_e32 v0, v0, v1
	v_ashrrev_i32_e32 v153, 6, v0
	v_add_u32_e32 v0, 32, v8
	v_ashrrev_i32_e32 v1, 31, v0
	v_lshlrev_b64 v[0:1], 11, v[0:1]
	v_ashrrev_i32_e32 v152, 6, v2
	v_lshl_add_u64 v[0:1], s[12:13], 0, v[0:1]
	v_and_b32_e32 v2, 0xc0, v2
	v_lshl_add_u64 v[0:1], v[0:1], 0, v[34:35]
	v_sub_u32_e32 v2, v9, v2
	global_load_dwordx4 v[36:39], v[0:1], off
	global_load_dwordx4 v[44:47], v[0:1], off offset:256
	v_ashrrev_i16_sdwa v0, v233, sext(v2) dst_sel:DWORD dst_unused:UNUSED_PAD src0_sel:DWORD src1_sel:BYTE_0
	v_bfe_i32 v154, v0, 0, 16
	v_add_u32_e32 v0, 48, v8
	v_lshlrev_b32_e32 v3, 3, v153
	v_ashrrev_i32_e32 v1, 31, v0
	v_and_b32_e32 v3, -16, v3
	v_lshlrev_b64 v[0:1], 11, v[0:1]
	v_add_u32_e32 v3, v152, v3
	v_and_b32_e32 v10, 3, v152
	v_lshl_add_u64 v[0:1], s[12:13], 0, v[0:1]
	v_and_or_b32 v10, v3, s5, v10
	v_lshl_add_u64 v[8:9], v[0:1], 0, v[34:35]
	v_readlane_b32 s5, v254, 33
	global_load_dwordx4 v[52:55], v[8:9], off
	global_load_dwordx4 v[60:63], v[8:9], off offset:256
	v_add_u32_e32 v8, s5, v144
	v_ashrrev_i32_e32 v9, 31, v8
	v_lshrrev_b32_e32 v11, 2, v3
	v_lshlrev_b32_e32 v16, 1, v3
	v_lshlrev_b64 v[8:9], 11, v[8:9]
	v_and_b32_e32 v11, 4, v11
	v_and_b32_e32 v16, 24, v16
	v_lshl_add_u64 v[8:9], s[12:13], 0, v[8:9]
	v_or3_b32 v10, v10, v11, v16
	v_lshl_add_u64 v[16:17], v[8:9], 0, v[34:35]
	v_readlane_b32 s5, v254, 34
	global_load_dwordx4 v[68:71], v[16:17], off
	global_load_dwordx4 v[76:79], v[16:17], off offset:256
	v_add_u32_e32 v16, s5, v144
	v_readlane_b32 s5, v254, 35
	v_ashrrev_i32_e32 v17, 31, v16
	v_lshlrev_b64 v[16:17], 11, v[16:17]
	v_add_u32_e32 v26, s5, v144
	v_readlane_b32 s5, v254, 37
	v_ashrrev_i32_e32 v27, 31, v26
	v_lshlrev_b64 v[26:27], 11, v[26:27]
	v_add_u32_e32 v40, s5, v144
	v_ashrrev_i32_e32 v41, 31, v40
	v_lshlrev_b64 v[40:41], 11, v[40:41]
	v_lshl_add_u64 v[16:17], s[12:13], 0, v[16:17]
	v_lshl_add_u64 v[26:27], s[12:13], 0, v[26:27]
	v_lshl_add_u64 v[40:41], s[12:13], 0, v[40:41]
	v_lshl_add_u64 v[24:25], v[16:17], 0, v[34:35]
	v_lshl_add_u64 v[32:33], v[26:27], 0, v[34:35]
	v_lshl_add_u64 v[42:43], v[40:41], 0, v[34:35]
	global_load_dwordx4 v[84:87], v[24:25], off
	global_load_dwordx4 v[92:95], v[24:25], off offset:256
	global_load_dwordx4 v[100:103], v[32:33], off
	global_load_dwordx4 v[108:111], v[32:33], off offset:256
	global_load_dwordx4 v[120:123], v[42:43], off
	global_load_dwordx4 v[128:131], v[42:43], off offset:256
	v_lshlrev_b32_e32 v11, 5, v153
	v_readlane_b32 s14, v254, 48
	v_and_b32_e32 v11, 32, v11
	v_readlane_b32 s15, v254, 49
	s_add_u32 s46, s55, s14
	v_add_lshl_u32 v2, v11, v154, 1
	s_addc_u32 s47, s56, s15
	s_add_i32 s58, s57, 0
	v_lshl_add_u32 v114, v10, 12, v2
	v_lshl_add_u32 v134, v3, 13, v2
	s_add_i32 m0, s58, 0x10000
	s_nop 0
	global_load_lds_dwordx4 v114, s[46:47]
	s_add_i32 m0, s58, 0x12000
	v_readlane_b32 s14, v254, 46
	v_readlane_b32 s15, v254, 47
	s_add_u32 s42, s48, s14
	s_addc_u32 s43, s54, s15
	s_add_u32 s14, s46, 0x80000
	global_load_lds_dwordx4 v112, s[46:47]
	s_addc_u32 s15, s47, 0
	s_add_i32 m0, s58, 0x14000
	s_add_i32 s59, s58, 0x2000
	global_load_lds_dwordx4 v114, s[14:15]
	s_add_i32 m0, s58, 0x16000
	v_mov_b32_e32 v113, v115
	global_load_lds_dwordx4 v112, s[14:15]
	s_mov_b32 m0, s58
	s_add_u32 s14, s42, 0x100000
	global_load_lds_dwordx4 v134, s[42:43]
	s_mov_b32 m0, s59
	s_addc_u32 s15, s43, 0
	s_add_i32 s60, s58, 0x4000
	global_load_lds_dwordx4 v132, s[42:43]
	s_mov_b32 m0, s60
	s_add_i32 s61, s58, 0x6000
	global_load_lds_dwordx4 v134, s[14:15]
	s_mov_b32 m0, s61
	v_mov_b32_e32 v135, v115
	global_load_lds_dwordx4 v132, s[14:15]
	s_waitcnt vmcnt(23)
; #define PG8_STAGE(bufoff, gbase, voff) do { _Pragma("unroll") for (int _i = 0; _i < 2; ++_i) \
;         __builtin_amdgcn_global_load_lds((const unsigned*)((const char*)(gbase) + (voff)[_i]), (PG8_LAS unsigned*)(lds + (bufoff) + ldsw + _i * 8192), 16, 0, 0); } while (0)
; #define PG8_BAR __builtin_amdgcn_s_barrier()
;     __device__ __forceinline__ void init(f32x4 (&acc)[2][2][4][2], const Unit& u, int wr, int wc, int fr, int fq) const {
;     ...
;                     else { const u32x4 r = *(const u32x4*)(xn + p); acc[ai][bj][m][0] = (f32x4){__uint_as_float(r.x << 16), __uint_as_float(r.x & 0xffff0000u), __uint_as_float(r.y << 16), __uint_as_float(r.y & 0xffff0000u)};
;                         acc[ai][bj][m][1] = (f32x4){__uint_as_float(r.z << 16), __uint_as_float(r.z & 0xffff0000u), __uint_as_float(r.w << 16), __uint_as_float(r.w & 0xffff0000u)}; } } }
; #pragma unroll
;         for (int ai = 0; ai < 2; ++ai)
; #pragma unroll
;             for (int bj = 0; bj < 2; ++bj)
; #pragma unroll
;                 for (int m = 0; m < 4; ++m) asm volatile("" : "+v"(acc[ai][bj][m][0]), "+v"(acc[ai][bj][m][1]));
; template <class Epi, class Sched, bool ALIGN_EPI = false, bool SP2 = false>
; __device__ __forceinline__ void gemm_phase(PG8_LAS unsigned char* lds, const Gemm g, const Sched& S, const Epi& E, const int tid_in) {
;     ...
;     const char* cA = (const char*)g.A + (size_t)cur.pm * tstepA + (size_t)(cur.pm >> 3) * g.abx; const char* cB = (const char*)g.Bt + (size_t)cur.pn * tstepB;
;     S.a_ready(cur);
;     if constexpr (SP2) {
;         PG8_STAGE(PG8_SB(0, 0), cB, voffB); PG8_STAGE(PG8_SB(0, 1), cB + hstepB, voffB); PG8_STAGE(PG8_SA(0, 0), cA, voffA); PG8_STAGE(PG8_SA(0, 1), cA + hstepA, voffA);
;         if (wr == 1) PG8_BAR;
	v_lshlrev_b32_e32 v0, 16, v4
	v_and_b32_e32 v1, 0xffff0000, v4
	v_lshlrev_b32_e32 v2, 16, v5
	v_and_b32_e32 v3, 0xffff0000, v5
	v_lshlrev_b32_e32 v4, 16, v6
	v_and_b32_e32 v5, 0xffff0000, v6
	v_lshlrev_b32_e32 v6, 16, v7
	v_and_b32_e32 v7, 0xffff0000, v7
	s_waitcnt vmcnt(22)
	v_lshlrev_b32_e32 v8, 16, v12
	v_and_b32_e32 v9, 0xffff0000, v12
	v_lshlrev_b32_e32 v10, 16, v13
	v_and_b32_e32 v11, 0xffff0000, v13
	v_lshlrev_b32_e32 v12, 16, v14
	v_and_b32_e32 v13, 0xffff0000, v14
	v_lshlrev_b32_e32 v14, 16, v15
	v_and_b32_e32 v15, 0xffff0000, v15
	s_waitcnt vmcnt(21)
	v_lshlrev_b32_e32 v16, 16, v20
	v_and_b32_e32 v17, 0xffff0000, v20
	v_lshlrev_b32_e32 v18, 16, v21
	v_and_b32_e32 v19, 0xffff0000, v21
	v_lshlrev_b32_e32 v20, 16, v22
	v_and_b32_e32 v21, 0xffff0000, v22
	v_lshlrev_b32_e32 v22, 16, v23
	v_and_b32_e32 v23, 0xffff0000, v23
	s_waitcnt vmcnt(20)
	v_lshlrev_b32_e32 v24, 16, v28
	v_and_b32_e32 v25, 0xffff0000, v28
	v_lshlrev_b32_e32 v26, 16, v29
	v_and_b32_e32 v27, 0xffff0000, v29
	v_lshlrev_b32_e32 v28, 16, v30
	v_and_b32_e32 v29, 0xffff0000, v30
	v_lshlrev_b32_e32 v30, 16, v31
	v_and_b32_e32 v31, 0xffff0000, v31
	s_waitcnt vmcnt(19)
	v_lshlrev_b32_e32 v32, 16, v36
	v_and_b32_e32 v33, 0xffff0000, v36
	v_lshlrev_b32_e32 v34, 16, v37
	v_and_b32_e32 v35, 0xffff0000, v37
	v_lshlrev_b32_e32 v36, 16, v38
	v_and_b32_e32 v37, 0xffff0000, v38
	v_lshlrev_b32_e32 v38, 16, v39
	v_and_b32_e32 v39, 0xffff0000, v39
	s_waitcnt vmcnt(18)
	v_lshlrev_b32_e32 v40, 16, v44
	v_and_b32_e32 v41, 0xffff0000, v44
	v_lshlrev_b32_e32 v42, 16, v45
	v_and_b32_e32 v43, 0xffff0000, v45
	v_lshlrev_b32_e32 v44, 16, v46
	v_and_b32_e32 v45, 0xffff0000, v46
	v_lshlrev_b32_e32 v46, 16, v47
	v_and_b32_e32 v47, 0xffff0000, v47
	s_waitcnt vmcnt(17)
	v_lshlrev_b32_e32 v48, 16, v52
	v_and_b32_e32 v49, 0xffff0000, v52
	v_lshlrev_b32_e32 v50, 16, v53
	v_and_b32_e32 v51, 0xffff0000, v53
	v_lshlrev_b32_e32 v52, 16, v54
	v_and_b32_e32 v53, 0xffff0000, v54
	v_lshlrev_b32_e32 v54, 16, v55
	v_and_b32_e32 v55, 0xffff0000, v55
	s_waitcnt vmcnt(16)
	v_lshlrev_b32_e32 v56, 16, v60
	v_and_b32_e32 v57, 0xffff0000, v60
	v_lshlrev_b32_e32 v58, 16, v61
	v_and_b32_e32 v59, 0xffff0000, v61
	v_lshlrev_b32_e32 v60, 16, v62
	v_and_b32_e32 v61, 0xffff0000, v62
	v_lshlrev_b32_e32 v62, 16, v63
	v_and_b32_e32 v63, 0xffff0000, v63
	s_waitcnt vmcnt(15)
	v_lshlrev_b32_e32 v64, 16, v68
	v_and_b32_e32 v65, 0xffff0000, v68
	v_lshlrev_b32_e32 v66, 16, v69
	v_and_b32_e32 v67, 0xffff0000, v69
	v_lshlrev_b32_e32 v68, 16, v70
	v_and_b32_e32 v69, 0xffff0000, v70
	v_lshlrev_b32_e32 v70, 16, v71
	v_and_b32_e32 v71, 0xffff0000, v71
	s_waitcnt vmcnt(14)
	v_lshlrev_b32_e32 v72, 16, v76
	v_and_b32_e32 v73, 0xffff0000, v76
	v_lshlrev_b32_e32 v74, 16, v77
	v_and_b32_e32 v75, 0xffff0000, v77
	v_lshlrev_b32_e32 v76, 16, v78
	v_and_b32_e32 v77, 0xffff0000, v78
	v_lshlrev_b32_e32 v78, 16, v79
	v_and_b32_e32 v79, 0xffff0000, v79
	s_waitcnt vmcnt(13)
	v_lshlrev_b32_e32 v80, 16, v84
	v_and_b32_e32 v81, 0xffff0000, v84
	v_lshlrev_b32_e32 v82, 16, v85
	v_and_b32_e32 v83, 0xffff0000, v85
	v_lshlrev_b32_e32 v84, 16, v86
	v_and_b32_e32 v85, 0xffff0000, v86
	v_lshlrev_b32_e32 v86, 16, v87
	v_and_b32_e32 v87, 0xffff0000, v87
	s_waitcnt vmcnt(12)
	v_lshlrev_b32_e32 v88, 16, v92
	v_and_b32_e32 v89, 0xffff0000, v92
	v_lshlrev_b32_e32 v90, 16, v93
	v_and_b32_e32 v91, 0xffff0000, v93
	v_lshlrev_b32_e32 v92, 16, v94
	v_and_b32_e32 v93, 0xffff0000, v94
	v_lshlrev_b32_e32 v94, 16, v95
	v_and_b32_e32 v95, 0xffff0000, v95
	s_waitcnt vmcnt(11)
	v_lshlrev_b32_e32 v96, 16, v100
	v_and_b32_e32 v97, 0xffff0000, v100
	v_lshlrev_b32_e32 v98, 16, v101
	v_and_b32_e32 v99, 0xffff0000, v101
	v_lshlrev_b32_e32 v100, 16, v102
	v_and_b32_e32 v101, 0xffff0000, v102
	v_lshlrev_b32_e32 v102, 16, v103
	v_and_b32_e32 v103, 0xffff0000, v103
	s_waitcnt vmcnt(10)
	v_lshlrev_b32_e32 v104, 16, v108
	v_and_b32_e32 v105, 0xffff0000, v108
	v_lshlrev_b32_e32 v106, 16, v109
	v_and_b32_e32 v107, 0xffff0000, v109
	v_lshlrev_b32_e32 v108, 16, v110
	v_and_b32_e32 v109, 0xffff0000, v110
	v_lshlrev_b32_e32 v110, 16, v111
	v_and_b32_e32 v111, 0xffff0000, v111
	s_waitcnt vmcnt(9)
	v_lshlrev_b32_e32 v116, 16, v120
	v_and_b32_e32 v117, 0xffff0000, v120
	v_lshlrev_b32_e32 v118, 16, v121
	v_and_b32_e32 v119, 0xffff0000, v121
	v_lshlrev_b32_e32 v120, 16, v122
	v_and_b32_e32 v121, 0xffff0000, v122
	v_lshlrev_b32_e32 v122, 16, v123
	v_and_b32_e32 v123, 0xffff0000, v123
	s_waitcnt vmcnt(8)
	v_lshlrev_b32_e32 v124, 16, v128
	v_and_b32_e32 v125, 0xffff0000, v128
	v_lshlrev_b32_e32 v126, 16, v129
	v_and_b32_e32 v127, 0xffff0000, v129
	v_lshlrev_b32_e32 v128, 16, v130
	v_and_b32_e32 v129, 0xffff0000, v130
	v_lshlrev_b32_e32 v130, 16, v131
	v_and_b32_e32 v131, 0xffff0000, v131
	v_mov_b32_e32 v133, v115
	s_cmp_eq_u32 s4, 1
	v_lshl_add_u64 v[142:143], s[46:47], 0, v[114:115]
	v_lshl_add_u64 v[140:141], s[46:47], 0, v[112:113]
	v_lshl_add_u64 v[136:137], s[42:43], 0, v[134:135]
	s_cselect_b64 s[18:19], -1, 0
	s_cmp_lg_u32 s4, 1
	v_lshl_add_u64 v[138:139], s[42:43], 0, v[132:133]
	s_cbranch_scc1 .LBB0_785
	s_barrier

;   __device__ __forceinline__ bool next(int i,AttnUnit&u)const{ const int p=vcu+(i>>1)*grid; if(p>=BATCH*NHEAD*4)return false; const int q=(p&31)+32*(p>>8), s=(q<32)?(q&3):(3-(q&3)); u.bh=((p>>5)&7)*NHEAD+((q<32)?(q>>2):(NHEAD-1-((q-32)>>2)));     u.qb=(i&1)?s:(NQB-1-s); u.reuse=i&1; return true; }
; template <class Epi, class Sched, bool ALIGN_EPI = false, bool SP2 = false>
; __device__ __forceinline__ void gemm_phase(PG8_LAS unsigned char* lds, const Gemm g, const Sched& S, const Epi& E, const int tid_in) {
;     ...
;         const bool has_next = S.next(ui + 1, nxt);
;         const char* nA = has_next ? (const char*)g.A + (size_t)nxt.pm * tstepA + (size_t)(nxt.pm >> 3) * g.abx : cA; const char* nB = has_next ? (const char*)g.Bt + (size_t)nxt.pn * tstepB : cB;
;         for (int t = 0; t < nt; t += 2) {
;             const bool last = (t == nt - 2);
;             const char* a1 = cA + (size_t)(t + 1) * kstep;
;             const char* a2 = last ? nA : cA + (size_t)(t + 2) * kstep; const char* b2 = last ? nB : cB + (size_t)(t + 2) * kstep;
;             const char* a3 = a2 + kstep; const char* b3 = b2 + kstep;
;             if (last && has_next) S.a_ready(nxt);
.LBB0_793:
	s_add_u32 s67, s46, 0x100
	s_addc_u32 s70, s47, 0
	s_ashr_i32 s27, s26, 31
	s_lshl_b64 s[14:15], s[26:27], 21
	s_add_u32 s40, s48, s14
	s_addc_u32 s41, s54, s15
	s_and_b64 s[14:15], s[38:39], exec
	s_cselect_b32 s14, s41, s43
	s_cselect_b32 s15, s40, s42
	s_ashr_i32 s25, s24, 31
	s_lshl_b64 s[28:29], s[24:25], 20
	s_add_u32 s28, s55, s28
	s_addc_u32 s29, s56, s29
	s_and_b64 s[50:51], s[38:39], exec
	s_cselect_b32 s25, s29, s47
	s_cselect_b32 s27, s28, s46
	s_add_u32 s46, s42, 0x100080
	s_addc_u32 s47, s43, 0
	v_lshl_add_u64 v[140:141], s[46:47], 0, v[136:137]
	v_lshl_add_u64 v[142:143], s[46:47], 0, v[138:139]
	s_mov_b32 s45, -2
	s_mov_b64 s[46:47], 0
	s_branch .LBB0_794
.Ltl_gout_2_s:
	global_load_dword v240, v241, s[50:51]
	s_branch .Ltl_gout_2_j

; #define PG8_STAGE(bufoff, gbase, voff) do { _Pragma("unroll") for (int _i = 0; _i < 2; ++_i) \
;         __builtin_amdgcn_global_load_lds((const unsigned*)((const char*)(gbase) + (voff)[_i]), (PG8_LAS unsigned*)(lds + (bufoff) + ldsw + _i * 8192), 16, 0, 0); } while (0)
; #define PG8_LDA(dst, b, h) do { _Pragma("unroll") for (int m = 0; m < 4; ++m) _Pragma("unroll") for (int k = 0; k < 2; ++k) dst[m][k] = *(const PG8_LAS bf16x8*)(lds + PG8_SA(b, h) + aoff + m * 2048 + k * 1024); } while (0)
; #define PG8_LDB(dst, b, h) do { _Pragma("unroll") for (int n = 0; n < 2; ++n) _Pragma("unroll") for (int k = 0; k < 2; ++k) dst[n][k] = *(const PG8_LAS bf16x8*)(lds + PG8_SB(b, h) + boff + n * 2048 + k * 1024); } while (0)
; #define PG8_MMA(ai, bj, At, Bt) do { __builtin_amdgcn_s_setprio(1); _Pragma("unroll") for (int m = 0; m < 4; ++m) _Pragma("unroll") for (int n = 0; n < 2; ++n) _Pragma("unroll") for (int k = 0; k < 2; ++k) \
;         acc[ai][bj][m][n] = __builtin_amdgcn_mfma_f32_16x16x32_bf16(Bt[n][k], At[m][k], acc[ai][bj][m][n], 0, 0, 0); __builtin_amdgcn_s_setprio(0); } while (0)
; #define PG8_WAIT_V(n) asm volatile("s_waitcnt vmcnt(" #n ")" ::: "memory")
; #define PG8_BAR __builtin_amdgcn_s_barrier()
; template <class Epi, class Sched, bool ALIGN_EPI = false, bool SP2 = false>
; __device__ __forceinline__ void gemm_phase(PG8_LAS unsigned char* lds, const Gemm g, const Sched& S, const Epi& E, const int tid_in) {
;     ...
;         for (int t = 0; t < nt; t += 2) {
;             const bool last = (t == nt - 2);
;             const char* a1 = cA + (size_t)(t + 1) * kstep;
;             const char* a2 = last ? nA : cA + (size_t)(t + 2) * kstep; const char* b2 = last ? nB : cB + (size_t)(t + 2) * kstep;
;             const char* a3 = a2 + kstep; const char* b3 = b2 + kstep;
;             if (last && has_next) S.a_ready(nxt);
;             if constexpr (SP2) {
;             PG8_LDB(B0, 0, 0); PG8_LDB(B1, 0, 1); PG8_SCHED; PG8_LDA(At, 0, 0); PG8_STAGE(PG8_SA(1, 1), a1 + hstepA, voffA);
;             PG8_WAIT_V(8); PG8_WAIT_L(0); PG8_BAR; PG8_MMA(0, 0, At, B0); PG8_MMA(0, 1, At, B1); PG8_BAR; PG8_SCHED;
;             PG8_LDA(At, 0, 1); PG8_STAGE(PG8_SB(0, 0), b2, voffB); PG8_STAGE(PG8_SB(0, 1), b2 + hstepB, voffB); PG8_STAGE(PG8_SA(0, 0), a2, voffA);
;             PG8_WAIT_V(8); PG8_WAIT_L(0); PG8_BAR; PG8_MMA(1, 0, At, B0); PG8_MMA(1, 1, At, B1); PG8_BAR; PG8_SCHED;
.LBB0_794:
	s_add_u32 s50, s42, s46
	s_addc_u32 s51, s43, s47
	s_add_u32 s50, s50, 0x100
	s_addc_u32 s51, s51, 0
	s_add_u32 s71, s67, s46
	s_addc_u32 s72, s70, s47
	s_add_i32 s73, 0, 0x10000
	s_cmpk_eq_i32 s46, 0xf00
	s_cselect_b32 s53, s14, s51
	s_cselect_b32 s52, s15, s50
	v_add_u32_e32 v151, s73, v145
	s_cselect_b32 s51, s25, s72
	s_cselect_b32 s50, s27, s71
	s_mov_b64 vcc, 0
	s_cmpk_lg_i32 s46, 0xf00
	s_cbranch_scc1 .Ltl_gout_keep
	s_cmp_lg_u32 s100, 0
	s_cbranch_scc1 .Ltl_gout_keep
	s_mov_b64 vcc, exec
.Ltl_gout_keep:
	s_add_i32 s71, 0, 0x14000
	ds_read_b128 v[152:155], v151
	ds_read_b128 v[156:159], v151 offset:1024
	ds_read_b128 v[160:163], v151 offset:2048
	ds_read_b128 v[164:167], v151 offset:3072
	v_add_u32_e32 v151, s71, v145
	ds_read_b128 v[168:171], v151
	ds_read_b128 v[172:175], v151 offset:1024
	ds_read_b128 v[176:179], v151 offset:2048
	ds_read_b128 v[180:183], v151 offset:3072
	v_lshl_add_u64 v[216:217], v[140:141], 0, s[46:47]
	s_add_i32 m0, s58, 0xc000
	ds_read_b128 v[184:187], v149
	ds_read_b128 v[188:191], v149 offset:1024
	ds_read_b128 v[192:195], v149 offset:2048
	ds_read_b128 v[196:199], v149 offset:3072
	ds_read_b128 v[200:203], v149 offset:4096
	ds_read_b128 v[204:207], v149 offset:5120
	ds_read_b128 v[208:211], v149 offset:6144
	ds_read_b128 v[212:215], v149 offset:7168
	global_load_lds_dwordx4 v[216:217], off
	v_lshl_add_u64 v[216:217], v[142:143], 0, s[46:47]
	s_add_i32 m0, s58, 0xe000
	s_nop 0
	global_load_lds_dwordx4 v[216:217], off
	s_waitcnt vmcnt(8)
	s_waitcnt lgkmcnt(0)
	s_barrier
	s_setprio 1
	s_waitcnt lgkmcnt(0)
	v_mfma_f32_16x16x32_bf16 v[0:3], v[152:155], v[184:187], v[0:3]
	v_mfma_f32_16x16x32_bf16 v[4:7], v[160:163], v[184:187], v[4:7]
	v_mfma_f32_16x16x32_bf16 v[16:19], v[152:155], v[192:195], v[16:19]
	v_mfma_f32_16x16x32_bf16 v[20:23], v[160:163], v[192:195], v[20:23]
	v_mfma_f32_16x16x32_bf16 v[32:35], v[152:155], v[200:203], v[32:35]
	v_mfma_f32_16x16x32_bf16 v[36:39], v[160:163], v[200:203], v[36:39]
	v_mfma_f32_16x16x32_bf16 v[48:51], v[152:155], v[208:211], v[48:51]
	v_mfma_f32_16x16x32_bf16 v[52:55], v[160:163], v[208:211], v[52:55]
	v_mfma_f32_16x16x32_bf16 v[0:3], v[156:159], v[188:191], v[0:3]
	v_mfma_f32_16x16x32_bf16 v[4:7], v[164:167], v[188:191], v[4:7]
	v_mfma_f32_16x16x32_bf16 v[16:19], v[156:159], v[196:199], v[16:19]
	v_mfma_f32_16x16x32_bf16 v[20:23], v[164:167], v[196:199], v[20:23]
	v_mfma_f32_16x16x32_bf16 v[32:35], v[156:159], v[204:207], v[32:35]
	v_mfma_f32_16x16x32_bf16 v[36:39], v[164:167], v[204:207], v[36:39]
	v_mfma_f32_16x16x32_bf16 v[48:51], v[156:159], v[212:215], v[48:51]
	v_mfma_f32_16x16x32_bf16 v[52:55], v[164:167], v[212:215], v[52:55]
	s_setprio 0
	s_setprio 1
	v_mfma_f32_16x16x32_bf16 v[8:11], v[168:171], v[184:187], v[8:11]
	v_mfma_f32_16x16x32_bf16 v[12:15], v[176:179], v[184:187], v[12:15]
	v_mfma_f32_16x16x32_bf16 v[24:27], v[168:171], v[192:195], v[24:27]
	v_mfma_f32_16x16x32_bf16 v[28:31], v[176:179], v[192:195], v[28:31]
	v_mfma_f32_16x16x32_bf16 v[40:43], v[168:171], v[200:203], v[40:43]
	v_mfma_f32_16x16x32_bf16 v[44:47], v[176:179], v[200:203], v[44:47]
	v_mfma_f32_16x16x32_bf16 v[56:59], v[168:171], v[208:211], v[56:59]
	v_mfma_f32_16x16x32_bf16 v[60:63], v[176:179], v[208:211], v[60:63]
	v_mfma_f32_16x16x32_bf16 v[8:11], v[172:175], v[188:191], v[8:11]
	v_mfma_f32_16x16x32_bf16 v[12:15], v[180:183], v[188:191], v[12:15]
	v_mfma_f32_16x16x32_bf16 v[24:27], v[172:175], v[196:199], v[24:27]
	v_mfma_f32_16x16x32_bf16 v[28:31], v[180:183], v[196:199], v[28:31]
	v_mfma_f32_16x16x32_bf16 v[40:43], v[172:175], v[204:207], v[40:43]
	v_mfma_f32_16x16x32_bf16 v[44:47], v[180:183], v[204:207], v[44:47]
	v_mfma_f32_16x16x32_bf16 v[56:59], v[172:175], v[212:215], v[56:59]
	v_mfma_f32_16x16x32_bf16 v[60:63], v[180:183], v[212:215], v[60:63]
	s_setprio 0
	s_barrier
	s_add_i32 s72, s73, s57
	v_lshl_add_u64 v[216:217], s[50:51], 0, v[114:115]
	s_mov_b32 m0, s72
	ds_read_b128 v[184:187], v149 offset:16384
	ds_read_b128 v[188:191], v149 offset:17408
	ds_read_b128 v[192:195], v149 offset:18432
	ds_read_b128 v[196:199], v149 offset:19456
	ds_read_b128 v[200:203], v149 offset:20480
	ds_read_b128 v[204:207], v149 offset:21504
	ds_read_b128 v[208:211], v149 offset:22528
	ds_read_b128 v[212:215], v149 offset:23552
	s_cbranch_vccnz .Ltl_gout_2_s
	global_load_lds_dwordx4 v[216:217], off
.Ltl_gout_2_j:
	s_add_i32 m0, s72, 0x2000
	s_add_u32 s72, s50, 0x80000
	v_lshl_add_u64 v[218:219], s[50:51], 0, v[112:113]
	s_addc_u32 s73, s51, 0
	s_add_i32 s71, s71, s57
	s_cbranch_vccnz .Ltl_gout_3_s
	global_load_lds_dwordx4 v[218:219], off
.Ltl_gout_3_j:
	v_lshl_add_u64 v[220:221], s[72:73], 0, v[114:115]
	s_mov_b32 m0, s71
	v_lshl_add_u64 v[222:223], s[52:53], 0, v[132:133]
	s_cbranch_vccnz .Ltl_gout_4_s
	global_load_lds_dwordx4 v[220:221], off
.Ltl_gout_4_j:
	v_lshl_add_u64 v[220:221], s[72:73], 0, v[112:113]
	s_add_i32 m0, s71, 0x2000
	s_nop 0
	s_cbranch_vccnz .Ltl_gout_5_s
	global_load_lds_dwordx4 v[220:221], off
.Ltl_gout_5_j:
	v_lshl_add_u64 v[220:221], s[52:53], 0, v[134:135]
	s_mov_b32 m0, s58
	s_nop 0
	s_cbranch_vccnz .Ltl_gout_6_s
	global_load_lds_dwordx4 v[220:221], off
.Ltl_gout_6_j:
	s_mov_b32 m0, s59
	s_nop 0
	s_cbranch_vccnz .Ltl_gout_7_s
	global_load_lds_dwordx4 v[222:223], off
; #define PG8_STAGE(bufoff, gbase, voff) do { _Pragma("unroll") for (int _i = 0; _i < 2; ++_i) \
;         __builtin_amdgcn_global_load_lds((const unsigned*)((const char*)(gbase) + (voff)[_i]), (PG8_LAS unsigned*)(lds + (bufoff) + ldsw + _i * 8192), 16, 0, 0); } while (0)
; #define PG8_LDA(dst, b, h) do { _Pragma("unroll") for (int m = 0; m < 4; ++m) _Pragma("unroll") for (int k = 0; k < 2; ++k) dst[m][k] = *(const PG8_LAS bf16x8*)(lds + PG8_SA(b, h) + aoff + m * 2048 + k * 1024); } while (0)
; #define PG8_LDB(dst, b, h) do { _Pragma("unroll") for (int n = 0; n < 2; ++n) _Pragma("unroll") for (int k = 0; k < 2; ++k) dst[n][k] = *(const PG8_LAS bf16x8*)(lds + PG8_SB(b, h) + boff + n * 2048 + k * 1024); } while (0)
; #define PG8_MMA(ai, bj, At, Bt) do { __builtin_amdgcn_s_setprio(1); _Pragma("unroll") for (int m = 0; m < 4; ++m) _Pragma("unroll") for (int n = 0; n < 2; ++n) _Pragma("unroll") for (int k = 0; k < 2; ++k) \
;         acc[ai][bj][m][n] = __builtin_amdgcn_mfma_f32_16x16x32_bf16(Bt[n][k], At[m][k], acc[ai][bj][m][n], 0, 0, 0); __builtin_amdgcn_s_setprio(0); } while (0)
; #define PG8_WAIT_V(n) asm volatile("s_waitcnt vmcnt(" #n ")" ::: "memory")
; #define PG8_WAIT_L(n) asm volatile("s_waitcnt lgkmcnt(" #n ")" ::: "memory")
; #define PG8_BAR __builtin_amdgcn_s_barrier()
; #define PG8_SCHED __builtin_amdgcn_sched_barrier(0)
; template <class Epi, class Sched, bool ALIGN_EPI = false, bool SP2 = false>
; __device__ __forceinline__ void gemm_phase(PG8_LAS unsigned char* lds, const Gemm g, const Sched& S, const Epi& E, const int tid_in) {
;     ...
;             PG8_WAIT_V(8); PG8_WAIT_L(0); PG8_BAR; PG8_MMA(0, 0, At, B0); PG8_MMA(0, 1, At, B1); PG8_BAR; PG8_SCHED;
;             PG8_LDA(At, 0, 1); PG8_STAGE(PG8_SB(0, 0), b2, voffB); PG8_STAGE(PG8_SB(0, 1), b2 + hstepB, voffB); PG8_STAGE(PG8_SA(0, 0), a2, voffA);
;             PG8_WAIT_V(8); PG8_WAIT_L(0); PG8_BAR; PG8_MMA(1, 0, At, B0); PG8_MMA(1, 1, At, B1); PG8_BAR; PG8_SCHED;
;             PG8_LDB(B0, 1, 0); PG8_LDB(B1, 1, 1); PG8_SCHED; PG8_LDA(At, 1, 0); PG8_STAGE(PG8_SA(0, 1), a2 + hstepA, voffA);
.Ltl_gout_7_j:
	s_waitcnt vmcnt(8)
	s_waitcnt lgkmcnt(0)
	s_barrier
	s_setprio 1
	s_waitcnt lgkmcnt(0)
	v_mfma_f32_16x16x32_bf16 v[64:67], v[152:155], v[184:187], v[64:67]
	v_mfma_f32_16x16x32_bf16 v[68:71], v[160:163], v[184:187], v[68:71]
	v_mfma_f32_16x16x32_bf16 v[80:83], v[152:155], v[192:195], v[80:83]
	v_mfma_f32_16x16x32_bf16 v[84:87], v[160:163], v[192:195], v[84:87]
	v_mfma_f32_16x16x32_bf16 v[96:99], v[152:155], v[200:203], v[96:99]
	v_mfma_f32_16x16x32_bf16 v[100:103], v[160:163], v[200:203], v[100:103]
	v_mfma_f32_16x16x32_bf16 v[116:119], v[152:155], v[208:211], v[116:119]
	v_mfma_f32_16x16x32_bf16 v[120:123], v[160:163], v[208:211], v[120:123]
	v_mfma_f32_16x16x32_bf16 v[64:67], v[156:159], v[188:191], v[64:67]
	v_mfma_f32_16x16x32_bf16 v[68:71], v[164:167], v[188:191], v[68:71]
	v_mfma_f32_16x16x32_bf16 v[80:83], v[156:159], v[196:199], v[80:83]
	v_mfma_f32_16x16x32_bf16 v[84:87], v[164:167], v[196:199], v[84:87]
	v_mfma_f32_16x16x32_bf16 v[96:99], v[156:159], v[204:207], v[96:99]
	v_mfma_f32_16x16x32_bf16 v[100:103], v[164:167], v[204:207], v[100:103]
	v_mfma_f32_16x16x32_bf16 v[116:119], v[156:159], v[212:215], v[116:119]
	v_mfma_f32_16x16x32_bf16 v[120:123], v[164:167], v[212:215], v[120:123]
	s_setprio 0
	s_setprio 1
	v_mfma_f32_16x16x32_bf16 v[72:75], v[168:171], v[184:187], v[72:75]
	v_mfma_f32_16x16x32_bf16 v[76:79], v[176:179], v[184:187], v[76:79]
	v_mfma_f32_16x16x32_bf16 v[88:91], v[168:171], v[192:195], v[88:91]
	v_mfma_f32_16x16x32_bf16 v[92:95], v[176:179], v[192:195], v[92:95]
	v_mfma_f32_16x16x32_bf16 v[104:107], v[168:171], v[200:203], v[104:107]
	v_mfma_f32_16x16x32_bf16 v[108:111], v[176:179], v[200:203], v[108:111]
	v_mfma_f32_16x16x32_bf16 v[124:127], v[168:171], v[208:211], v[124:127]
	v_mfma_f32_16x16x32_bf16 v[128:131], v[176:179], v[208:211], v[128:131]
	v_mfma_f32_16x16x32_bf16 v[72:75], v[172:175], v[188:191], v[72:75]
	v_mfma_f32_16x16x32_bf16 v[76:79], v[180:183], v[188:191], v[76:79]
	v_mfma_f32_16x16x32_bf16 v[88:91], v[172:175], v[196:199], v[88:91]
	v_mfma_f32_16x16x32_bf16 v[92:95], v[180:183], v[196:199], v[92:95]
	v_mfma_f32_16x16x32_bf16 v[104:107], v[172:175], v[204:207], v[104:107]
	v_mfma_f32_16x16x32_bf16 v[108:111], v[180:183], v[204:207], v[108:111]
	v_mfma_f32_16x16x32_bf16 v[124:127], v[172:175], v[212:215], v[124:127]
	v_mfma_f32_16x16x32_bf16 v[128:131], v[180:183], v[212:215], v[128:131]
	s_setprio 0
	s_barrier
	s_add_i32 s71, 0, 0x18000
	v_add_u32_e32 v151, s71, v145
	s_add_i32 s72, 0, 0x1c000
	ds_read_b128 v[152:155], v151
	ds_read_b128 v[156:159], v151 offset:1024
	ds_read_b128 v[160:163], v151 offset:2048
	ds_read_b128 v[164:167], v151 offset:3072
	v_add_u32_e32 v151, s72, v145
	ds_read_b128 v[168:171], v151
	ds_read_b128 v[172:175], v151 offset:1024
	ds_read_b128 v[176:179], v151 offset:2048
	ds_read_b128 v[180:183], v151 offset:3072
	s_add_u32 s52, s52, 0x100000
	s_addc_u32 s53, s53, 0
	s_mov_b32 m0, s60
	v_lshl_add_u64 v[224:225], s[52:53], 0, v[134:135]
	ds_read_b128 v[184:187], v149 offset:32768
	ds_read_b128 v[188:191], v149 offset:33792
	ds_read_b128 v[192:195], v149 offset:34816
	ds_read_b128 v[196:199], v149 offset:35840
	ds_read_b128 v[200:203], v149 offset:36864
	ds_read_b128 v[204:207], v149 offset:37888
	ds_read_b128 v[208:211], v149 offset:38912
	ds_read_b128 v[212:215], v149 offset:39936
	s_cbranch_vccnz .Ltl_gout_8_s
	global_load_lds_dwordx4 v[224:225], off
.Ltl_gout_8_j:
	v_lshl_add_u64 v[224:225], s[52:53], 0, v[132:133]
	s_mov_b32 m0, s61
	s_nop 0
	s_cbranch_vccnz .Ltl_gout_9_s
	global_load_lds_dwordx4 v[224:225], off
; #define PG8_STAGE(bufoff, gbase, voff) do { _Pragma("unroll") for (int _i = 0; _i < 2; ++_i) \
;         __builtin_amdgcn_global_load_lds((const unsigned*)((const char*)(gbase) + (voff)[_i]), (PG8_LAS unsigned*)(lds + (bufoff) + ldsw + _i * 8192), 16, 0, 0); } while (0)
; #define PG8_LDA(dst, b, h) do { _Pragma("unroll") for (int m = 0; m < 4; ++m) _Pragma("unroll") for (int k = 0; k < 2; ++k) dst[m][k] = *(const PG8_LAS bf16x8*)(lds + PG8_SA(b, h) + aoff + m * 2048 + k * 1024); } while (0)
; #define PG8_WAIT_V(n) asm volatile("s_waitcnt vmcnt(" #n ")" ::: "memory")
; #define PG8_WAIT_L(n) asm volatile("s_waitcnt lgkmcnt(" #n ")" ::: "memory")
; #define PG8_BAR __builtin_amdgcn_s_barrier()
; template <class Epi, class Sched, bool ALIGN_EPI = false, bool SP2 = false>
; __device__ __forceinline__ void gemm_phase(PG8_LAS unsigned char* lds, const Gemm g, const Sched& S, const Epi& E, const int tid_in) {
;     ...
;         for (int t = 0; t < nt; t += 2) {
;             const bool last = (t == nt - 2);
;             const char* a1 = cA + (size_t)(t + 1) * kstep;
;             const char* a2 = last ? nA : cA + (size_t)(t + 2) * kstep; const char* b2 = last ? nB : cB + (size_t)(t + 2) * kstep;
;             const char* a3 = a2 + kstep; const char* b3 = b2 + kstep;
;             if (last && has_next) S.a_ready(nxt);
;             if constexpr (SP2) {
;             PG8_LDB(B0, 0, 0); PG8_LDB(B1, 0, 1); PG8_SCHED; PG8_LDA(At, 0, 0); PG8_STAGE(PG8_SA(1, 1), a1 + hstepA, voffA);
;             PG8_WAIT_V(8); PG8_WAIT_L(0); PG8_BAR; PG8_MMA(0, 0, At, B0); PG8_MMA(0, 1, At, B1); PG8_BAR; PG8_SCHED;
;             PG8_LDA(At, 0, 1); PG8_STAGE(PG8_SB(0, 0), b2, voffB); PG8_STAGE(PG8_SB(0, 1), b2 + hstepB, voffB); PG8_STAGE(PG8_SA(0, 0), a2, voffA);
;             PG8_WAIT_V(8); PG8_WAIT_L(0); PG8_BAR; PG8_MMA(1, 0, At, B0); PG8_MMA(1, 1, At, B1); PG8_BAR; PG8_SCHED;
;             PG8_LDB(B0, 1, 0); PG8_LDB(B1, 1, 1); PG8_SCHED; PG8_LDA(At, 1, 0); PG8_STAGE(PG8_SA(0, 1), a2 + hstepA, voffA);
;             PG8_WAIT_V(8); PG8_WAIT_L(0); PG8_BAR; PG8_MMA(0, 0, At, B0); PG8_MMA(0, 1, At, B1); PG8_BAR; PG8_SCHED;
;             PG8_LDA(At, 1, 1); PG8_STAGE(PG8_SB(1, 0), b3, voffB); PG8_STAGE(PG8_SB(1, 1), b3 + hstepB, voffB); PG8_STAGE(PG8_SA(1, 0), a3, voffA);
;             PG8_WAIT_V(8); PG8_WAIT_L(0); PG8_BAR; PG8_MMA(1, 0, At, B0); PG8_MMA(1, 1, At, B1); PG8_BAR; PG8_SCHED;
.Ltl_gout_9_j:
	s_waitcnt vmcnt(8)
	s_waitcnt lgkmcnt(0)
	s_barrier
	s_setprio 1
	s_waitcnt lgkmcnt(0)
	v_mfma_f32_16x16x32_bf16 v[0:3], v[152:155], v[184:187], v[0:3]
	v_mfma_f32_16x16x32_bf16 v[4:7], v[160:163], v[184:187], v[4:7]
	v_mfma_f32_16x16x32_bf16 v[16:19], v[152:155], v[192:195], v[16:19]
	v_mfma_f32_16x16x32_bf16 v[20:23], v[160:163], v[192:195], v[20:23]
	v_mfma_f32_16x16x32_bf16 v[32:35], v[152:155], v[200:203], v[32:35]
	v_mfma_f32_16x16x32_bf16 v[36:39], v[160:163], v[200:203], v[36:39]
	v_mfma_f32_16x16x32_bf16 v[48:51], v[152:155], v[208:211], v[48:51]
	v_mfma_f32_16x16x32_bf16 v[52:55], v[160:163], v[208:211], v[52:55]
	v_mfma_f32_16x16x32_bf16 v[0:3], v[156:159], v[188:191], v[0:3]
	v_mfma_f32_16x16x32_bf16 v[4:7], v[164:167], v[188:191], v[4:7]
	v_mfma_f32_16x16x32_bf16 v[16:19], v[156:159], v[196:199], v[16:19]
	v_mfma_f32_16x16x32_bf16 v[20:23], v[164:167], v[196:199], v[20:23]
	v_mfma_f32_16x16x32_bf16 v[32:35], v[156:159], v[204:207], v[32:35]
	v_mfma_f32_16x16x32_bf16 v[36:39], v[164:167], v[204:207], v[36:39]
	v_mfma_f32_16x16x32_bf16 v[48:51], v[156:159], v[212:215], v[48:51]
	v_mfma_f32_16x16x32_bf16 v[52:55], v[164:167], v[212:215], v[52:55]
	s_setprio 0
	s_setprio 1
	v_mfma_f32_16x16x32_bf16 v[8:11], v[168:171], v[184:187], v[8:11]
	v_mfma_f32_16x16x32_bf16 v[12:15], v[176:179], v[184:187], v[12:15]
	v_mfma_f32_16x16x32_bf16 v[24:27], v[168:171], v[192:195], v[24:27]
	v_mfma_f32_16x16x32_bf16 v[28:31], v[176:179], v[192:195], v[28:31]
	v_mfma_f32_16x16x32_bf16 v[40:43], v[168:171], v[200:203], v[40:43]
	v_mfma_f32_16x16x32_bf16 v[44:47], v[176:179], v[200:203], v[44:47]
	v_mfma_f32_16x16x32_bf16 v[56:59], v[168:171], v[208:211], v[56:59]
	v_mfma_f32_16x16x32_bf16 v[60:63], v[176:179], v[208:211], v[60:63]
	v_mfma_f32_16x16x32_bf16 v[8:11], v[172:175], v[188:191], v[8:11]
	v_mfma_f32_16x16x32_bf16 v[12:15], v[180:183], v[188:191], v[12:15]
	v_mfma_f32_16x16x32_bf16 v[24:27], v[172:175], v[196:199], v[24:27]
	v_mfma_f32_16x16x32_bf16 v[28:31], v[180:183], v[196:199], v[28:31]
	v_mfma_f32_16x16x32_bf16 v[40:43], v[172:175], v[204:207], v[40:43]
	v_mfma_f32_16x16x32_bf16 v[44:47], v[180:183], v[204:207], v[44:47]
	v_mfma_f32_16x16x32_bf16 v[56:59], v[172:175], v[212:215], v[56:59]
	v_mfma_f32_16x16x32_bf16 v[60:63], v[180:183], v[212:215], v[60:63]
	s_setprio 0
	s_barrier
	s_add_i32 s52, s71, s57
	v_lshl_add_u64 v[216:217], v[216:217], 0, s[10:11]
	s_mov_b32 m0, s52
	ds_read_b128 v[184:187], v149 offset:49152
	ds_read_b128 v[188:191], v149 offset:50176
	ds_read_b128 v[192:195], v149 offset:51200
	ds_read_b128 v[196:199], v149 offset:52224
	ds_read_b128 v[200:203], v149 offset:53248
	ds_read_b128 v[204:207], v149 offset:54272
	ds_read_b128 v[208:211], v149 offset:55296
	ds_read_b128 v[212:215], v149 offset:56320
	s_cbranch_vccnz .Ltl_gout_10_s
	global_load_lds_dwordx4 v[216:217], off
.Ltl_gout_10_j:
	s_add_i32 m0, s52, 0x2000
	s_add_u32 s50, s50, 0x80080
	v_lshl_add_u64 v[216:217], v[218:219], 0, s[10:11]
	s_addc_u32 s51, s51, 0
	s_add_i32 s52, s72, s57
	s_cbranch_vccnz .Ltl_gout_11_s
	global_load_lds_dwordx4 v[216:217], off
.Ltl_gout_11_j:
	v_lshl_add_u64 v[216:217], s[50:51], 0, v[114:115]
	s_mov_b32 m0, s52
	s_nop 0
	s_cbranch_vccnz .Ltl_gout_12_s
	global_load_lds_dwordx4 v[216:217], off
.Ltl_gout_12_j:
	v_lshl_add_u64 v[216:217], s[50:51], 0, v[112:113]
	s_add_i32 m0, s52, 0x2000
	s_nop 0
	s_cbranch_vccnz .Ltl_gout_13_s
	global_load_lds_dwordx4 v[216:217], off
.Ltl_gout_13_j:
	v_lshl_add_u64 v[216:217], v[220:221], 0, s[10:11]
	s_mov_b32 m0, s62
	s_nop 0
	s_cbranch_vccnz .Ltl_gout_14_s
	global_load_lds_dwordx4 v[216:217], off
.Ltl_gout_14_j:
	v_lshl_add_u64 v[216:217], v[222:223], 0, s[10:11]
	s_mov_b32 m0, s63
	s_nop 0
	s_cbranch_vccnz .Ltl_gout_15_s
	global_load_lds_dwordx4 v[216:217], off
.Ltl_gout_15_j:
	s_waitcnt vmcnt(8)
	s_waitcnt lgkmcnt(0)
	s_barrier
	s_setprio 1
	s_waitcnt lgkmcnt(0)
	v_mfma_f32_16x16x32_bf16 v[64:67], v[152:155], v[184:187], v[64:67]
	v_mfma_f32_16x16x32_bf16 v[68:71], v[160:163], v[184:187], v[68:71]
	v_mfma_f32_16x16x32_bf16 v[80:83], v[152:155], v[192:195], v[80:83]
	v_mfma_f32_16x16x32_bf16 v[84:87], v[160:163], v[192:195], v[84:87]
	v_mfma_f32_16x16x32_bf16 v[96:99], v[152:155], v[200:203], v[96:99]
	v_mfma_f32_16x16x32_bf16 v[100:103], v[160:163], v[200:203], v[100:103]
	v_mfma_f32_16x16x32_bf16 v[116:119], v[152:155], v[208:211], v[116:119]
	v_mfma_f32_16x16x32_bf16 v[120:123], v[160:163], v[208:211], v[120:123]
	v_mfma_f32_16x16x32_bf16 v[64:67], v[156:159], v[188:191], v[64:67]
	v_mfma_f32_16x16x32_bf16 v[68:71], v[164:167], v[188:191], v[68:71]
	v_mfma_f32_16x16x32_bf16 v[80:83], v[156:159], v[196:199], v[80:83]
	v_mfma_f32_16x16x32_bf16 v[84:87], v[164:167], v[196:199], v[84:87]
	v_mfma_f32_16x16x32_bf16 v[96:99], v[156:159], v[204:207], v[96:99]
	v_mfma_f32_16x16x32_bf16 v[100:103], v[164:167], v[204:207], v[100:103]
	v_mfma_f32_16x16x32_bf16 v[116:119], v[156:159], v[212:215], v[116:119]
	v_mfma_f32_16x16x32_bf16 v[120:123], v[164:167], v[212:215], v[120:123]
	s_setprio 0
	s_setprio 1
	v_mfma_f32_16x16x32_bf16 v[72:75], v[168:171], v[184:187], v[72:75]
	v_mfma_f32_16x16x32_bf16 v[76:79], v[176:179], v[184:187], v[76:79]
	v_mfma_f32_16x16x32_bf16 v[88:91], v[168:171], v[192:195], v[88:91]
	v_mfma_f32_16x16x32_bf16 v[92:95], v[176:179], v[192:195], v[92:95]
	v_mfma_f32_16x16x32_bf16 v[104:107], v[168:171], v[200:203], v[104:107]
	v_mfma_f32_16x16x32_bf16 v[108:111], v[176:179], v[200:203], v[108:111]
	v_mfma_f32_16x16x32_bf16 v[124:127], v[168:171], v[208:211], v[124:127]
	v_mfma_f32_16x16x32_bf16 v[128:131], v[176:179], v[208:211], v[128:131]
	v_mfma_f32_16x16x32_bf16 v[72:75], v[172:175], v[188:191], v[72:75]
	v_mfma_f32_16x16x32_bf16 v[76:79], v[180:183], v[188:191], v[76:79]
	v_mfma_f32_16x16x32_bf16 v[88:91], v[172:175], v[196:199], v[88:91]
	v_mfma_f32_16x16x32_bf16 v[92:95], v[180:183], v[196:199], v[92:95]
	v_mfma_f32_16x16x32_bf16 v[104:107], v[172:175], v[204:207], v[104:107]
	v_mfma_f32_16x16x32_bf16 v[108:111], v[180:183], v[204:207], v[108:111]
	v_mfma_f32_16x16x32_bf16 v[124:127], v[172:175], v[212:215], v[124:127]
	v_mfma_f32_16x16x32_bf16 v[128:131], v[180:183], v[212:215], v[128:131]
	s_setprio 0
	s_barrier
	s_add_i32 s45, s45, 2
	s_add_u32 s46, s46, 0x100
	s_addc_u32 s47, s47, 0
	s_cmp_gt_u32 s45, 29
	s_cbranch_scc0 .LBB0_794
	s_and_b64 vcc, exec, s[22:23]
	s_cbranch_vccz .LBB0_797
	s_barrier

; #define LAS __attribute__((address_space(3)))
; #define ws KWS(F)
; #define out KOUT(F)
; #define xs ((float*)(KWS(F) + WS_XS))
; #define IN_PH() (lo <= ph && ph < hi && relaunder(F))
; #define END_PH() do { if (ph + 1 < hi) { bar.bar = (unsigned*)(KWS(F) + WS_CTL) + CW_BAR; xcd_barrier(bar, xlocal); } } while (0)
; __global__ void __launch_bounds__(NWAVES * 64, 2) mk_fwd(Args args) {
;     ...
;         if (IN_PH()) { pg8::Gemm g{BIG, (const bf16*)(ws + WS_W2 + L * 8 * MiB), M, D, FF, FF, 0}; pg8::StaticOrder S; S.init(M, D, F.G, F.cid);
;             { pg8::EpiRes E{(const float*)nullptr, (L == 3) ? out : (float*)nullptr, XN, xs, D, (LAS float*)(F.lds + 131072 + 256)}; pg8::gemm_phase<pg8::EpiRes, pg8::StaticOrder, true, PG8_SP2>(F.lds, g, S, E, F.tid); } END_PH(); } ++ph;
.LBB0_959:
	s_andn2_b64 vcc, exec, s[0:1]
	s_cbranch_vccnz .LBB0_1063
	v_mbcnt_lo_u32_b32 v241, -1, 0
	v_mbcnt_hi_u32_b32 v241, -1, v241
	v_lshlrev_b32_e32 v241, 2, v241
	v_readlane_b32 s0, v255, 5
	s_mov_b32 s4, -1
	s_cmp_lg_u32 s0, 3
	s_mov_b64 s[12:13], 0
	v_readlane_b32 s1, v255, 6
	s_cbranch_scc1 .LBB0_962
	s_load_dwordx2 s[12:13], s[94:95], 0x80

;   __device__ __forceinline__ bool next(int i,AttnUnit&u)const{ const int p=vcu+(i>>1)*grid; if(p>=BATCH*NHEAD*4)return false; const int q=(p&31)+32*(p>>8), s=(q<32)?(q&3):(3-(q&3)); u.bh=((p>>5)&7)*NHEAD+((q<32)?(q>>2):(NHEAD-1-((q-32)>>2)));     u.qb=(i&1)?s:(NQB-1-s); u.reuse=i&1; return true; }
; template <class Epi, class Sched, bool ALIGN_EPI = false, bool SP2 = false>
; __device__ __forceinline__ void gemm_phase(PG8_LAS unsigned char* lds, const Gemm g, const Sched& S, const Epi& E, const int tid_in) {
;     ...
;         const bool has_next = S.next(ui + 1, nxt);
;         const char* nA = has_next ? (const char*)g.A + (size_t)nxt.pm * tstepA + (size_t)(nxt.pm >> 3) * g.abx : cA; const char* nB = has_next ? (const char*)g.Bt + (size_t)nxt.pn * tstepB : cB;
;         for (int t = 0; t < nt; t += 2) {
;             const bool last = (t == nt - 2);
;             const char* a1 = cA + (size_t)(t + 1) * kstep;
;             const char* a2 = last ? nA : cA + (size_t)(t + 2) * kstep; const char* b2 = last ? nB : cB + (size_t)(t + 2) * kstep;
;             const char* a3 = a2 + kstep; const char* b3 = b2 + kstep;
;             if (last && has_next) S.a_ready(nxt);
.LBB0_973:
	s_add_u32 s73, s40, 0x100
	s_addc_u32 s74, s41, 0
	s_ashr_i32 s43, s42, 31
	s_lshl_b64 s[14:15], s[42:43], 21
	s_add_u32 s46, s58, s14
	s_addc_u32 s47, s59, s15
	s_and_b64 s[14:15], s[38:39], exec
	s_cselect_b32 s14, s47, s51
	s_cselect_b32 s15, s46, s50
	s_ashr_i32 s29, s28, 31
	s_lshl_b64 s[44:45], s[28:29], 21
	s_add_u32 s44, s60, s44
	s_addc_u32 s45, s61, s45
	s_and_b64 s[54:55], s[38:39], exec
	s_cselect_b32 s29, s45, s41
	s_cselect_b32 s43, s44, s40
	s_add_u32 s40, s50, 0x100080
	s_addc_u32 s41, s51, 0
	v_lshl_add_u64 v[140:141], s[40:41], 0, v[136:137]
	v_lshl_add_u64 v[142:143], s[40:41], 0, v[138:139]
	s_mov_b32 s53, -2
	s_mov_b64 s[40:41], 0
	s_branch .LBB0_974

; #define PG8_STAGE(bufoff, gbase, voff) do { _Pragma("unroll") for (int _i = 0; _i < 2; ++_i) \
;         __builtin_amdgcn_global_load_lds((const unsigned*)((const char*)(gbase) + (voff)[_i]), (PG8_LAS unsigned*)(lds + (bufoff) + ldsw + _i * 8192), 16, 0, 0); } while (0)
; #define PG8_LDA(dst, b, h) do { _Pragma("unroll") for (int m = 0; m < 4; ++m) _Pragma("unroll") for (int k = 0; k < 2; ++k) dst[m][k] = *(const PG8_LAS bf16x8*)(lds + PG8_SA(b, h) + aoff + m * 2048 + k * 1024); } while (0)
; #define PG8_LDB(dst, b, h) do { _Pragma("unroll") for (int n = 0; n < 2; ++n) _Pragma("unroll") for (int k = 0; k < 2; ++k) dst[n][k] = *(const PG8_LAS bf16x8*)(lds + PG8_SB(b, h) + boff + n * 2048 + k * 1024); } while (0)
; #define PG8_MMA(ai, bj, At, Bt) do { __builtin_amdgcn_s_setprio(1); _Pragma("unroll") for (int m = 0; m < 4; ++m) _Pragma("unroll") for (int n = 0; n < 2; ++n) _Pragma("unroll") for (int k = 0; k < 2; ++k) \
;         acc[ai][bj][m][n] = __builtin_amdgcn_mfma_f32_16x16x32_bf16(Bt[n][k], At[m][k], acc[ai][bj][m][n], 0, 0, 0); __builtin_amdgcn_s_setprio(0); } while (0)
; #define PG8_WAIT_V(n) asm volatile("s_waitcnt vmcnt(" #n ")" ::: "memory")
; #define PG8_BAR __builtin_amdgcn_s_barrier()
; template <class Epi, class Sched, bool ALIGN_EPI = false, bool SP2 = false>
; __device__ __forceinline__ void gemm_phase(PG8_LAS unsigned char* lds, const Gemm g, const Sched& S, const Epi& E, const int tid_in) {
;     ...
;         for (int t = 0; t < nt; t += 2) {
;             const bool last = (t == nt - 2);
;             const char* a1 = cA + (size_t)(t + 1) * kstep;
;             const char* a2 = last ? nA : cA + (size_t)(t + 2) * kstep; const char* b2 = last ? nB : cB + (size_t)(t + 2) * kstep;
;             const char* a3 = a2 + kstep; const char* b3 = b2 + kstep;
;             if (last && has_next) S.a_ready(nxt);
;             if constexpr (SP2) {
;             PG8_LDB(B0, 0, 0); PG8_LDB(B1, 0, 1); PG8_SCHED; PG8_LDA(At, 0, 0); PG8_STAGE(PG8_SA(1, 1), a1 + hstepA, voffA);
;             PG8_WAIT_V(8); PG8_WAIT_L(0); PG8_BAR; PG8_MMA(0, 0, At, B0); PG8_MMA(0, 1, At, B1); PG8_BAR; PG8_SCHED;
;             PG8_LDA(At, 0, 1); PG8_STAGE(PG8_SB(0, 0), b2, voffB); PG8_STAGE(PG8_SB(0, 1), b2 + hstepB, voffB); PG8_STAGE(PG8_SA(0, 0), a2, voffA);
;             PG8_WAIT_V(8); PG8_WAIT_L(0); PG8_BAR; PG8_MMA(1, 0, At, B0); PG8_MMA(1, 1, At, B1); PG8_BAR; PG8_SCHED;
.LBB0_974:
	s_add_u32 s54, s50, s40
	s_addc_u32 s55, s51, s41
	s_add_u32 s54, s54, 0x100
	s_addc_u32 s55, s55, 0
	s_add_u32 s75, s73, s40
	s_addc_u32 s76, s74, s41
	s_add_i32 s77, 0, 0x10000
	s_cmpk_eq_i32 s40, 0x1f00
	s_cselect_b32 s57, s14, s55
	s_cselect_b32 s56, s15, s54
	v_add_u32_e32 v155, s77, v149
	s_cselect_b32 s55, s29, s76
	s_cselect_b32 s54, s43, s75
	s_mov_b64 vcc, 0
	s_cmpk_lg_i32 s40, 0x1f00
	s_cbranch_scc1 .Ltl_down_keep
	s_cmp_lg_u32 s100, 0
	s_cbranch_scc1 .Ltl_down_keep
	s_mov_b64 vcc, exec
.Ltl_down_keep:
	s_add_i32 s75, 0, 0x14000
	ds_read_b128 v[144:147], v155
	ds_read_b128 v[156:159], v155 offset:1024
	ds_read_b128 v[160:163], v155 offset:2048
	ds_read_b128 v[164:167], v155 offset:3072
	v_add_u32_e32 v155, s75, v149
	ds_read_b128 v[168:171], v155
	ds_read_b128 v[172:175], v155 offset:1024
	ds_read_b128 v[176:179], v155 offset:2048
	ds_read_b128 v[180:183], v155 offset:3072
	v_lshl_add_u64 v[216:217], v[140:141], 0, s[40:41]
	s_add_i32 m0, s62, 0xc000
	ds_read_b128 v[184:187], v153
	ds_read_b128 v[188:191], v153 offset:1024
	ds_read_b128 v[192:195], v153 offset:2048
	ds_read_b128 v[196:199], v153 offset:3072
	ds_read_b128 v[200:203], v153 offset:4096
	ds_read_b128 v[204:207], v153 offset:5120
	ds_read_b128 v[208:211], v153 offset:6144
	ds_read_b128 v[212:215], v153 offset:7168
	global_load_lds_dwordx4 v[216:217], off
	v_lshl_add_u64 v[216:217], v[142:143], 0, s[40:41]
	s_add_i32 m0, s62, 0xe000
	s_nop 0
	global_load_lds_dwordx4 v[216:217], off
	s_waitcnt vmcnt(8)
	s_waitcnt lgkmcnt(0)
	s_barrier
	s_setprio 1
	s_waitcnt lgkmcnt(0)
	v_mfma_f32_16x16x32_bf16 v[0:3], v[144:147], v[184:187], v[0:3]
	v_mfma_f32_16x16x32_bf16 v[4:7], v[160:163], v[184:187], v[4:7]
	v_mfma_f32_16x16x32_bf16 v[16:19], v[144:147], v[192:195], v[16:19]
	v_mfma_f32_16x16x32_bf16 v[20:23], v[160:163], v[192:195], v[20:23]
	v_mfma_f32_16x16x32_bf16 v[32:35], v[144:147], v[200:203], v[32:35]
	v_mfma_f32_16x16x32_bf16 v[36:39], v[160:163], v[200:203], v[36:39]
	v_mfma_f32_16x16x32_bf16 v[48:51], v[144:147], v[208:211], v[48:51]
	v_mfma_f32_16x16x32_bf16 v[52:55], v[160:163], v[208:211], v[52:55]
	v_mfma_f32_16x16x32_bf16 v[0:3], v[156:159], v[188:191], v[0:3]
	v_mfma_f32_16x16x32_bf16 v[4:7], v[164:167], v[188:191], v[4:7]
	v_mfma_f32_16x16x32_bf16 v[16:19], v[156:159], v[196:199], v[16:19]
	v_mfma_f32_16x16x32_bf16 v[20:23], v[164:167], v[196:199], v[20:23]
	v_mfma_f32_16x16x32_bf16 v[32:35], v[156:159], v[204:207], v[32:35]
	v_mfma_f32_16x16x32_bf16 v[36:39], v[164:167], v[204:207], v[36:39]
	v_mfma_f32_16x16x32_bf16 v[48:51], v[156:159], v[212:215], v[48:51]
	v_mfma_f32_16x16x32_bf16 v[52:55], v[164:167], v[212:215], v[52:55]
	s_setprio 0
	s_setprio 1
	v_mfma_f32_16x16x32_bf16 v[8:11], v[168:171], v[184:187], v[8:11]
	v_mfma_f32_16x16x32_bf16 v[12:15], v[176:179], v[184:187], v[12:15]
	v_mfma_f32_16x16x32_bf16 v[24:27], v[168:171], v[192:195], v[24:27]
	v_mfma_f32_16x16x32_bf16 v[28:31], v[176:179], v[192:195], v[28:31]
	v_mfma_f32_16x16x32_bf16 v[40:43], v[168:171], v[200:203], v[40:43]
	v_mfma_f32_16x16x32_bf16 v[44:47], v[176:179], v[200:203], v[44:47]
	v_mfma_f32_16x16x32_bf16 v[56:59], v[168:171], v[208:211], v[56:59]
	v_mfma_f32_16x16x32_bf16 v[60:63], v[176:179], v[208:211], v[60:63]
	v_mfma_f32_16x16x32_bf16 v[8:11], v[172:175], v[188:191], v[8:11]
	v_mfma_f32_16x16x32_bf16 v[12:15], v[180:183], v[188:191], v[12:15]
	v_mfma_f32_16x16x32_bf16 v[24:27], v[172:175], v[196:199], v[24:27]
	v_mfma_f32_16x16x32_bf16 v[28:31], v[180:183], v[196:199], v[28:31]
	v_mfma_f32_16x16x32_bf16 v[40:43], v[172:175], v[204:207], v[40:43]
	v_mfma_f32_16x16x32_bf16 v[44:47], v[180:183], v[204:207], v[44:47]
	v_mfma_f32_16x16x32_bf16 v[56:59], v[172:175], v[212:215], v[56:59]
	v_mfma_f32_16x16x32_bf16 v[60:63], v[180:183], v[212:215], v[60:63]
	s_setprio 0
	s_barrier
	s_add_i32 s76, s77, s48
	v_lshl_add_u64 v[216:217], s[54:55], 0, v[114:115]
	s_mov_b32 m0, s76
	ds_read_b128 v[184:187], v153 offset:16384
	ds_read_b128 v[188:191], v153 offset:17408
	ds_read_b128 v[192:195], v153 offset:18432
	ds_read_b128 v[196:199], v153 offset:19456
	ds_read_b128 v[200:203], v153 offset:20480
	ds_read_b128 v[204:207], v153 offset:21504
	ds_read_b128 v[208:211], v153 offset:22528
	ds_read_b128 v[212:215], v153 offset:23552
	s_cbranch_vccnz .Ltl_down_2_s
	global_load_lds_dwordx4 v[216:217], off
.Ltl_down_2_j:
	s_add_i32 m0, s76, 0x2000
	s_add_u32 s76, s54, 0x100000
	v_lshl_add_u64 v[218:219], s[54:55], 0, v[112:113]
	s_addc_u32 s77, s55, 0
	s_add_i32 s75, s75, s48
	s_cbranch_vccnz .Ltl_down_3_s
	global_load_lds_dwordx4 v[218:219], off
.Ltl_down_3_j:
	v_lshl_add_u64 v[220:221], s[76:77], 0, v[114:115]
	s_mov_b32 m0, s75
	v_lshl_add_u64 v[222:223], s[56:57], 0, v[132:133]
	s_cbranch_vccnz .Ltl_down_4_s
	global_load_lds_dwordx4 v[220:221], off
.Ltl_down_4_j:
	v_lshl_add_u64 v[220:221], s[76:77], 0, v[112:113]
	s_add_i32 m0, s75, 0x2000
	s_nop 0
	s_cbranch_vccnz .Ltl_down_5_s
	global_load_lds_dwordx4 v[220:221], off
.Ltl_down_5_j:
	v_lshl_add_u64 v[220:221], s[56:57], 0, v[134:135]
	s_mov_b32 m0, s62
	s_nop 0
	s_cbranch_vccnz .Ltl_down_6_s
	global_load_lds_dwordx4 v[220:221], off
.Ltl_down_6_j:
	s_mov_b32 m0, s63
	s_nop 0
	s_cbranch_vccnz .Ltl_down_7_s
	global_load_lds_dwordx4 v[222:223], off
; #define PG8_STAGE(bufoff, gbase, voff) do { _Pragma("unroll") for (int _i = 0; _i < 2; ++_i) \
;         __builtin_amdgcn_global_load_lds((const unsigned*)((const char*)(gbase) + (voff)[_i]), (PG8_LAS unsigned*)(lds + (bufoff) + ldsw + _i * 8192), 16, 0, 0); } while (0)
; #define PG8_LDA(dst, b, h) do { _Pragma("unroll") for (int m = 0; m < 4; ++m) _Pragma("unroll") for (int k = 0; k < 2; ++k) dst[m][k] = *(const PG8_LAS bf16x8*)(lds + PG8_SA(b, h) + aoff + m * 2048 + k * 1024); } while (0)
; #define PG8_LDB(dst, b, h) do { _Pragma("unroll") for (int n = 0; n < 2; ++n) _Pragma("unroll") for (int k = 0; k < 2; ++k) dst[n][k] = *(const PG8_LAS bf16x8*)(lds + PG8_SB(b, h) + boff + n * 2048 + k * 1024); } while (0)
; #define PG8_MMA(ai, bj, At, Bt) do { __builtin_amdgcn_s_setprio(1); _Pragma("unroll") for (int m = 0; m < 4; ++m) _Pragma("unroll") for (int n = 0; n < 2; ++n) _Pragma("unroll") for (int k = 0; k < 2; ++k) \
;         acc[ai][bj][m][n] = __builtin_amdgcn_mfma_f32_16x16x32_bf16(Bt[n][k], At[m][k], acc[ai][bj][m][n], 0, 0, 0); __builtin_amdgcn_s_setprio(0); } while (0)
; #define PG8_WAIT_V(n) asm volatile("s_waitcnt vmcnt(" #n ")" ::: "memory")
; #define PG8_WAIT_L(n) asm volatile("s_waitcnt lgkmcnt(" #n ")" ::: "memory")
; #define PG8_BAR __builtin_amdgcn_s_barrier()
; #define PG8_SCHED __builtin_amdgcn_sched_barrier(0)
; template <class Epi, class Sched, bool ALIGN_EPI = false, bool SP2 = false>
; __device__ __forceinline__ void gemm_phase(PG8_LAS unsigned char* lds, const Gemm g, const Sched& S, const Epi& E, const int tid_in) {
;     ...
;             PG8_WAIT_V(8); PG8_WAIT_L(0); PG8_BAR; PG8_MMA(1, 0, At, B0); PG8_MMA(1, 1, At, B1); PG8_BAR; PG8_SCHED;
;             PG8_LDB(B0, 1, 0); PG8_LDB(B1, 1, 1); PG8_SCHED; PG8_LDA(At, 1, 0); PG8_STAGE(PG8_SA(0, 1), a2 + hstepA, voffA);
;             PG8_WAIT_V(8); PG8_WAIT_L(0); PG8_BAR; PG8_MMA(0, 0, At, B0); PG8_MMA(0, 1, At, B1); PG8_BAR; PG8_SCHED;
;             PG8_LDA(At, 1, 1); PG8_STAGE(PG8_SB(1, 0), b3, voffB); PG8_STAGE(PG8_SB(1, 1), b3 + hstepB, voffB); PG8_STAGE(PG8_SA(1, 0), a3, voffA);
;             PG8_WAIT_V(8); PG8_WAIT_L(0); PG8_BAR; PG8_MMA(1, 0, At, B0); PG8_MMA(1, 1, At, B1); PG8_BAR; PG8_SCHED;
.Ltl_down_7_j:
	s_waitcnt vmcnt(8)
	s_waitcnt lgkmcnt(0)
	s_barrier
	s_setprio 1
	s_waitcnt lgkmcnt(0)
	v_mfma_f32_16x16x32_bf16 v[64:67], v[144:147], v[184:187], v[64:67]
	v_mfma_f32_16x16x32_bf16 v[68:71], v[160:163], v[184:187], v[68:71]
	v_mfma_f32_16x16x32_bf16 v[80:83], v[144:147], v[192:195], v[80:83]
	v_mfma_f32_16x16x32_bf16 v[84:87], v[160:163], v[192:195], v[84:87]
	v_mfma_f32_16x16x32_bf16 v[96:99], v[144:147], v[200:203], v[96:99]
	v_mfma_f32_16x16x32_bf16 v[100:103], v[160:163], v[200:203], v[100:103]
	v_mfma_f32_16x16x32_bf16 v[116:119], v[144:147], v[208:211], v[116:119]
	v_mfma_f32_16x16x32_bf16 v[120:123], v[160:163], v[208:211], v[120:123]
	v_mfma_f32_16x16x32_bf16 v[64:67], v[156:159], v[188:191], v[64:67]
	v_mfma_f32_16x16x32_bf16 v[68:71], v[164:167], v[188:191], v[68:71]
	v_mfma_f32_16x16x32_bf16 v[80:83], v[156:159], v[196:199], v[80:83]
	v_mfma_f32_16x16x32_bf16 v[84:87], v[164:167], v[196:199], v[84:87]
	v_mfma_f32_16x16x32_bf16 v[96:99], v[156:159], v[204:207], v[96:99]
	v_mfma_f32_16x16x32_bf16 v[100:103], v[164:167], v[204:207], v[100:103]
	v_mfma_f32_16x16x32_bf16 v[116:119], v[156:159], v[212:215], v[116:119]
	v_mfma_f32_16x16x32_bf16 v[120:123], v[164:167], v[212:215], v[120:123]
	s_setprio 0
	s_setprio 1
	v_mfma_f32_16x16x32_bf16 v[72:75], v[168:171], v[184:187], v[72:75]
	v_mfma_f32_16x16x32_bf16 v[76:79], v[176:179], v[184:187], v[76:79]
	v_mfma_f32_16x16x32_bf16 v[88:91], v[168:171], v[192:195], v[88:91]
	v_mfma_f32_16x16x32_bf16 v[92:95], v[176:179], v[192:195], v[92:95]
	v_mfma_f32_16x16x32_bf16 v[104:107], v[168:171], v[200:203], v[104:107]
	v_mfma_f32_16x16x32_bf16 v[108:111], v[176:179], v[200:203], v[108:111]
	v_mfma_f32_16x16x32_bf16 v[124:127], v[168:171], v[208:211], v[124:127]
	v_mfma_f32_16x16x32_bf16 v[128:131], v[176:179], v[208:211], v[128:131]
	v_mfma_f32_16x16x32_bf16 v[72:75], v[172:175], v[188:191], v[72:75]
	v_mfma_f32_16x16x32_bf16 v[76:79], v[180:183], v[188:191], v[76:79]
	v_mfma_f32_16x16x32_bf16 v[88:91], v[172:175], v[196:199], v[88:91]
	v_mfma_f32_16x16x32_bf16 v[92:95], v[180:183], v[196:199], v[92:95]
	v_mfma_f32_16x16x32_bf16 v[104:107], v[172:175], v[204:207], v[104:107]
	v_mfma_f32_16x16x32_bf16 v[108:111], v[180:183], v[204:207], v[108:111]
	v_mfma_f32_16x16x32_bf16 v[124:127], v[172:175], v[212:215], v[124:127]
	v_mfma_f32_16x16x32_bf16 v[128:131], v[180:183], v[212:215], v[128:131]
	s_setprio 0
	s_barrier
	s_add_i32 s75, 0, 0x18000
	v_add_u32_e32 v155, s75, v149
	s_add_i32 s76, 0, 0x1c000
	ds_read_b128 v[144:147], v155
	ds_read_b128 v[156:159], v155 offset:1024
	ds_read_b128 v[160:163], v155 offset:2048
	ds_read_b128 v[164:167], v155 offset:3072
	v_add_u32_e32 v155, s76, v149
	ds_read_b128 v[168:171], v155
	ds_read_b128 v[172:175], v155 offset:1024
	ds_read_b128 v[176:179], v155 offset:2048
	ds_read_b128 v[180:183], v155 offset:3072
	s_add_u32 s56, s56, 0x100000
	s_addc_u32 s57, s57, 0
	s_mov_b32 m0, s64
	v_lshl_add_u64 v[224:225], s[56:57], 0, v[134:135]
	ds_read_b128 v[184:187], v153 offset:32768
	ds_read_b128 v[188:191], v153 offset:33792
	ds_read_b128 v[192:195], v153 offset:34816
	ds_read_b128 v[196:199], v153 offset:35840
	ds_read_b128 v[200:203], v153 offset:36864
	ds_read_b128 v[204:207], v153 offset:37888
	ds_read_b128 v[208:211], v153 offset:38912
	ds_read_b128 v[212:215], v153 offset:39936
	s_cbranch_vccnz .Ltl_down_8_s
	global_load_lds_dwordx4 v[224:225], off
.Ltl_down_8_j:
	v_lshl_add_u64 v[224:225], s[56:57], 0, v[132:133]
	s_mov_b32 m0, s65
	s_nop 0
	s_cbranch_vccnz .Ltl_down_9_s
	global_load_lds_dwordx4 v[224:225], off
.Ltl_down_9_j:
	s_waitcnt vmcnt(8)
	s_waitcnt lgkmcnt(0)
	s_barrier
	s_setprio 1
	s_waitcnt lgkmcnt(0)
	v_mfma_f32_16x16x32_bf16 v[0:3], v[144:147], v[184:187], v[0:3]
	v_mfma_f32_16x16x32_bf16 v[4:7], v[160:163], v[184:187], v[4:7]
	v_mfma_f32_16x16x32_bf16 v[16:19], v[144:147], v[192:195], v[16:19]
	v_mfma_f32_16x16x32_bf16 v[20:23], v[160:163], v[192:195], v[20:23]
	v_mfma_f32_16x16x32_bf16 v[32:35], v[144:147], v[200:203], v[32:35]
	v_mfma_f32_16x16x32_bf16 v[36:39], v[160:163], v[200:203], v[36:39]
	v_mfma_f32_16x16x32_bf16 v[48:51], v[144:147], v[208:211], v[48:51]
	v_mfma_f32_16x16x32_bf16 v[52:55], v[160:163], v[208:211], v[52:55]
	v_mfma_f32_16x16x32_bf16 v[0:3], v[156:159], v[188:191], v[0:3]
	v_mfma_f32_16x16x32_bf16 v[4:7], v[164:167], v[188:191], v[4:7]
	v_mfma_f32_16x16x32_bf16 v[16:19], v[156:159], v[196:199], v[16:19]
	v_mfma_f32_16x16x32_bf16 v[20:23], v[164:167], v[196:199], v[20:23]
	v_mfma_f32_16x16x32_bf16 v[32:35], v[156:159], v[204:207], v[32:35]
	v_mfma_f32_16x16x32_bf16 v[36:39], v[164:167], v[204:207], v[36:39]
	v_mfma_f32_16x16x32_bf16 v[48:51], v[156:159], v[212:215], v[48:51]
	v_mfma_f32_16x16x32_bf16 v[52:55], v[164:167], v[212:215], v[52:55]
	s_setprio 0
	s_setprio 1
	v_mfma_f32_16x16x32_bf16 v[8:11], v[168:171], v[184:187], v[8:11]
	v_mfma_f32_16x16x32_bf16 v[12:15], v[176:179], v[184:187], v[12:15]
	v_mfma_f32_16x16x32_bf16 v[24:27], v[168:171], v[192:195], v[24:27]
	v_mfma_f32_16x16x32_bf16 v[28:31], v[176:179], v[192:195], v[28:31]
	v_mfma_f32_16x16x32_bf16 v[40:43], v[168:171], v[200:203], v[40:43]
	v_mfma_f32_16x16x32_bf16 v[44:47], v[176:179], v[200:203], v[44:47]
	v_mfma_f32_16x16x32_bf16 v[56:59], v[168:171], v[208:211], v[56:59]
	v_mfma_f32_16x16x32_bf16 v[60:63], v[176:179], v[208:211], v[60:63]
	v_mfma_f32_16x16x32_bf16 v[8:11], v[172:175], v[188:191], v[8:11]
	v_mfma_f32_16x16x32_bf16 v[12:15], v[180:183], v[188:191], v[12:15]
	v_mfma_f32_16x16x32_bf16 v[24:27], v[172:175], v[196:199], v[24:27]
	v_mfma_f32_16x16x32_bf16 v[28:31], v[180:183], v[196:199], v[28:31]
	v_mfma_f32_16x16x32_bf16 v[40:43], v[172:175], v[204:207], v[40:43]
	v_mfma_f32_16x16x32_bf16 v[44:47], v[180:183], v[204:207], v[44:47]
	v_mfma_f32_16x16x32_bf16 v[56:59], v[172:175], v[212:215], v[56:59]
	v_mfma_f32_16x16x32_bf16 v[60:63], v[180:183], v[212:215], v[60:63]
	s_setprio 0
	s_barrier
	s_add_i32 s56, s75, s48
	v_lshl_add_u64 v[216:217], v[216:217], 0, s[10:11]
	s_mov_b32 m0, s56
	ds_read_b128 v[184:187], v153 offset:49152
	ds_read_b128 v[188:191], v153 offset:50176
	ds_read_b128 v[192:195], v153 offset:51200
	ds_read_b128 v[196:199], v153 offset:52224
	ds_read_b128 v[200:203], v153 offset:53248
	ds_read_b128 v[204:207], v153 offset:54272
	ds_read_b128 v[208:211], v153 offset:55296
	ds_read_b128 v[212:215], v153 offset:56320
	s_cbranch_vccnz .Ltl_down_10_s
	global_load_lds_dwordx4 v[216:217], off
.Ltl_down_10_j:
	s_add_i32 m0, s56, 0x2000
	s_add_u32 s54, s54, 0x100080
	v_lshl_add_u64 v[216:217], v[218:219], 0, s[10:11]
	s_addc_u32 s55, s55, 0
	s_add_i32 s56, s76, s48
	s_cbranch_vccnz .Ltl_down_11_s
	global_load_lds_dwordx4 v[216:217], off
.Ltl_down_11_j:
	v_lshl_add_u64 v[216:217], s[54:55], 0, v[114:115]
	s_mov_b32 m0, s56
	s_nop 0
	s_cbranch_vccnz .Ltl_down_12_s
	global_load_lds_dwordx4 v[216:217], off
.Ltl_down_12_j:
	v_lshl_add_u64 v[216:217], s[54:55], 0, v[112:113]
	s_add_i32 m0, s56, 0x2000
	s_nop 0
	s_cbranch_vccnz .Ltl_down_13_s
	global_load_lds_dwordx4 v[216:217], off

; #define PG8_STAGE(bufoff, gbase, voff) do { _Pragma("unroll") for (int _i = 0; _i < 2; ++_i) \
;         __builtin_amdgcn_global_load_lds((const unsigned*)((const char*)(gbase) + (voff)[_i]), (PG8_LAS unsigned*)(lds + (bufoff) + ldsw + _i * 8192), 16, 0, 0); } while (0)
; #define PG8_LDA(dst, b, h) do { _Pragma("unroll") for (int m = 0; m < 4; ++m) _Pragma("unroll") for (int k = 0; k < 2; ++k) dst[m][k] = *(const PG8_LAS bf16x8*)(lds + PG8_SA(b, h) + aoff + m * 2048 + k * 1024); } while (0)
; #define PG8_MMA(ai, bj, At, Bt) do { __builtin_amdgcn_s_setprio(1); _Pragma("unroll") for (int m = 0; m < 4; ++m) _Pragma("unroll") for (int n = 0; n < 2; ++n) _Pragma("unroll") for (int k = 0; k < 2; ++k) \
;         acc[ai][bj][m][n] = __builtin_amdgcn_mfma_f32_16x16x32_bf16(Bt[n][k], At[m][k], acc[ai][bj][m][n], 0, 0, 0); __builtin_amdgcn_s_setprio(0); } while (0)
; #define PG8_WAIT_V(n) asm volatile("s_waitcnt vmcnt(" #n ")" ::: "memory")
; #define PG8_WAIT_L(n) asm volatile("s_waitcnt lgkmcnt(" #n ")" ::: "memory")
; #define PG8_BAR __builtin_amdgcn_s_barrier()
; #define PG8_SCHED __builtin_amdgcn_sched_barrier(0)
; template <class Epi, class Sched, bool ALIGN_EPI = false, bool SP2 = false>
; __device__ __forceinline__ void gemm_phase(PG8_LAS unsigned char* lds, const Gemm g, const Sched& S, const Epi& E, const int tid_in) {
;     ...
;             PG8_WAIT_V(8); PG8_WAIT_L(0); PG8_BAR; PG8_MMA(0, 0, At, B0); PG8_MMA(0, 1, At, B1); PG8_BAR; PG8_SCHED;
;             PG8_LDA(At, 1, 1); PG8_STAGE(PG8_SB(1, 0), b3, voffB); PG8_STAGE(PG8_SB(1, 1), b3 + hstepB, voffB); PG8_STAGE(PG8_SA(1, 0), a3, voffA);
;             PG8_WAIT_V(8); PG8_WAIT_L(0); PG8_BAR; PG8_MMA(1, 0, At, B0); PG8_MMA(1, 1, At, B1); PG8_BAR; PG8_SCHED;
;     ...
;         if constexpr (ALIGN_EPI) { if (wr == 0) PG8_BAR; }
.Ltl_down_15_j:
	s_waitcnt vmcnt(8)
	s_waitcnt lgkmcnt(0)
	s_barrier
	s_setprio 1
	s_waitcnt lgkmcnt(0)
	v_mfma_f32_16x16x32_bf16 v[64:67], v[144:147], v[184:187], v[64:67]
	v_mfma_f32_16x16x32_bf16 v[68:71], v[160:163], v[184:187], v[68:71]
	v_mfma_f32_16x16x32_bf16 v[80:83], v[144:147], v[192:195], v[80:83]
	v_mfma_f32_16x16x32_bf16 v[84:87], v[160:163], v[192:195], v[84:87]
	v_mfma_f32_16x16x32_bf16 v[96:99], v[144:147], v[200:203], v[96:99]
	v_mfma_f32_16x16x32_bf16 v[100:103], v[160:163], v[200:203], v[100:103]
	v_mfma_f32_16x16x32_bf16 v[116:119], v[144:147], v[208:211], v[116:119]
	v_mfma_f32_16x16x32_bf16 v[120:123], v[160:163], v[208:211], v[120:123]
	v_mfma_f32_16x16x32_bf16 v[64:67], v[156:159], v[188:191], v[64:67]
	v_mfma_f32_16x16x32_bf16 v[68:71], v[164:167], v[188:191], v[68:71]
	v_mfma_f32_16x16x32_bf16 v[80:83], v[156:159], v[196:199], v[80:83]
	v_mfma_f32_16x16x32_bf16 v[84:87], v[164:167], v[196:199], v[84:87]
	v_mfma_f32_16x16x32_bf16 v[96:99], v[156:159], v[204:207], v[96:99]
	v_mfma_f32_16x16x32_bf16 v[100:103], v[164:167], v[204:207], v[100:103]
	v_mfma_f32_16x16x32_bf16 v[116:119], v[156:159], v[212:215], v[116:119]
	v_mfma_f32_16x16x32_bf16 v[120:123], v[164:167], v[212:215], v[120:123]
	s_setprio 0
	s_setprio 1
	v_mfma_f32_16x16x32_bf16 v[72:75], v[168:171], v[184:187], v[72:75]
	v_mfma_f32_16x16x32_bf16 v[76:79], v[176:179], v[184:187], v[76:79]
	v_mfma_f32_16x16x32_bf16 v[88:91], v[168:171], v[192:195], v[88:91]
	v_mfma_f32_16x16x32_bf16 v[92:95], v[176:179], v[192:195], v[92:95]
	v_mfma_f32_16x16x32_bf16 v[104:107], v[168:171], v[200:203], v[104:107]
	v_mfma_f32_16x16x32_bf16 v[108:111], v[176:179], v[200:203], v[108:111]
	v_mfma_f32_16x16x32_bf16 v[124:127], v[168:171], v[208:211], v[124:127]
	v_mfma_f32_16x16x32_bf16 v[128:131], v[176:179], v[208:211], v[128:131]
	v_mfma_f32_16x16x32_bf16 v[72:75], v[172:175], v[188:191], v[72:75]
	v_mfma_f32_16x16x32_bf16 v[76:79], v[180:183], v[188:191], v[76:79]
	v_mfma_f32_16x16x32_bf16 v[88:91], v[172:175], v[196:199], v[88:91]
	v_mfma_f32_16x16x32_bf16 v[92:95], v[180:183], v[196:199], v[92:95]
	v_mfma_f32_16x16x32_bf16 v[104:107], v[172:175], v[204:207], v[104:107]
	v_mfma_f32_16x16x32_bf16 v[108:111], v[180:183], v[204:207], v[108:111]
	v_mfma_f32_16x16x32_bf16 v[124:127], v[172:175], v[212:215], v[124:127]
	v_mfma_f32_16x16x32_bf16 v[128:131], v[180:183], v[212:215], v[128:131]
	s_setprio 0
	s_barrier
	s_add_i32 s53, s53, 2
	s_add_u32 s40, s40, 0x100
	s_addc_u32 s41, s41, 0
	s_cmp_gt_u32 s53, 61
	s_cbranch_scc0 .LBB0_974
	s_and_b64 vcc, exec, s[24:25]
	s_cbranch_vccz .LBB0_977
	s_barrier
